# prompt-attention role barrier split into early arrive + late wait, tile DMA moved behind the arrive, decode score reads pipelined, P10 norm-partial prefetch, P8 residual epilogue: loads hoisted + 16-b
# speedup vs baseline: 1.0142x; 1.0142x over previous
.LBB0_939:
	v_add_f32_e32 v68, 0, v68
	v_add_f32_e32 v69, 0, v69
	v_add_f32_e32 v68, v70, v68
	v_add_f32_e32 v69, v71, v69
	s_add_i32 s8, s16, 3
	v_add_f32_e32 v68, v72, v68
	v_add_f32_e32 v69, v73, v69
	s_lshr_b32 s8, s8, 1
	v_add_f32_e32 v68, v74, v68
	v_add_f32_e32 v69, v75, v69
	s_min_u32 s8, s8, 63
	v_add_f32_e32 v68, v76, v68
	v_add_f32_e32 v69, v77, v69
	v_readlane_b32 s8, v222, s8
	v_add_f32_e32 v68, v78, v68
	v_add_f32_e32 v69, v79, v69
	s_ashr_i32 s9, s8, 31
	v_add_f32_e32 v68, v80, v68
	v_add_f32_e32 v69, v81, v69
	s_lshl_b64 s[8:9], s[8:9], 7
	v_add_f32_e32 v68, v82, v68
	v_add_f32_e32 v69, v83, v69
	s_or_b32 s8, s8, 64
	v_add_f32_e32 v68, v69, v68
	s_lshl_b64 s[14:15], s[8:9], 9
	v_add_f32_e32 v3, v3, v68
	v_lshl_add_u64 v[68:69], v[190:191], 0, s[14:15]
	v_add_co_u32_e32 v70, vcc, s26, v68
	global_load_dwordx4 v[144:147], v[68:69], off nt
	s_nop 0
	v_addc_co_u32_e32 v71, vcc, 0, v69, vcc
	global_load_dwordx4 v[136:139], v[70:71], off offset:-4096 nt
	global_load_dwordx4 v[116:119], v[70:71], off nt
	v_add_co_u32_e32 v70, vcc, s24, v68
	s_lshl_b64 s[8:9], s[8:9], 7
	s_nop 0
	v_addc_co_u32_e32 v71, vcc, 0, v69, vcc
	global_load_dwordx4 v[124:127], v[70:71], off offset:-4096 nt
	global_load_dwordx4 v[108:111], v[70:71], off nt
	v_add_co_u32_e32 v70, vcc, s28, v68
	v_mov_b32_e32 v238, v208
	s_nop 0
	v_addc_co_u32_e32 v71, vcc, 0, v69, vcc
	v_add_co_u32_e32 v68, vcc, s29, v68
	global_load_dwordx4 v[128:131], v[70:71], off offset:-4096 nt
	global_load_dwordx4 v[112:115], v[70:71], off nt
	v_addc_co_u32_e32 v69, vcc, 0, v69, vcc
	global_load_dwordx4 v[132:135], v[68:69], off nt
	v_lshl_add_u64 v[68:69], v[192:193], 0, s[8:9]
	global_load_dwordx4 v[120:123], v[68:69], off nt
	v_add_co_u32_e32 v68, vcc, s25, v68
	s_nop 1
	v_addc_co_u32_e32 v69, vcc, 0, v69, vcc
	global_load_dwordx4 v[140:143], v[68:69], off nt
	v_mov_b32_e32 v68, v209
	s_nop 0
	v_lshlrev_b32_e32 v236, 5, v68
	v_add_u32_e32 v68, v233, v236
	ds_read_b128 v[68:71], v68
	v_xad_u32 v210, v236, 32, v233
	ds_read_b128 v[210:213], v210
	v_xad_u32 v240, v236, 64, v233
	ds_read_b128 v[240:243], v240
	v_xad_u32 v244, v236, s31, v233
	ds_read_b128 v[244:247], v244
	v_xad_u32 v248, v236, s34, v233
	ds_read_b128 v[248:251], v248
	s_waitcnt lgkmcnt(4)
	v_mfma_f32_32x32x16_bf16 v[68:83], v[68:71], v[84:87], 0
	s_waitcnt lgkmcnt(3)
	v_mfma_f32_32x32x16_bf16 v[68:83], v[210:213], v[88:91], v[68:83]
	v_xad_u32 v210, v236, s22, v233
	ds_read_b128 v[210:213], v210
	s_waitcnt lgkmcnt(3)
	v_mfma_f32_32x32x16_bf16 v[68:83], v[240:243], v[92:95], v[68:83]
	v_xor_b32_e32 v240, 0xc0, v236
	v_add_u32_e32 v240, v233, v240
	ds_read_b128 v[240:243], v240
	s_waitcnt lgkmcnt(3)
	v_mfma_f32_32x32x16_bf16 v[68:83], v[244:247], v[96:99], v[68:83]
	v_xor_b32_e32 v244, 0xc0, v236
	v_add_u32_e32 v244, v223, v244
	ds_read_b128 v[244:247], v244
	s_waitcnt lgkmcnt(3)
	v_mfma_f32_32x32x16_bf16 v[68:83], v[248:251], v[100:103], v[68:83]
	v_xor_b32_e32 v248, 0xe0, v236
	v_add_u32_e32 v248, v233, v248
	ds_read_b128 v[248:251], v248
	s_waitcnt lgkmcnt(3)
	v_mfma_f32_32x32x16_bf16 v[68:83], v[210:213], v[104:107], v[68:83]
	v_xor_b32_e32 v210, 0xe0, v236
	v_add_u32_e32 v210, v223, v210
	ds_read_b128 v[210:213], v210
	s_waitcnt lgkmcnt(2)
	v_mfma_f32_32x32x16_bf16 v[68:83], v[240:243], v[244:247], v[68:83]
	v_add_u32_e32 v240, s35, v224
	ds_read_b128 v[240:243], v240
	ds_read_b128 v[244:247], v227
	s_waitcnt lgkmcnt(2)
	v_mfma_f32_32x32x16_bf16 v[68:83], v[248:251], v[210:213], v[68:83]
	v_add_u32_e32 v248, s35, v225
	ds_read_b128 v[248:251], v248
	ds_read_b128 v[210:213], v228
	s_waitcnt lgkmcnt(2)
	v_mfma_f32_32x32x16_bf16 v[68:83], v[240:243], v[244:247], v[68:83]
	s_waitcnt lgkmcnt(0)
	v_mfma_f32_32x32x16_bf16 v[68:83], v[248:251], v[210:213], v[68:83]
	v_max3_f32 v210, v68, v69, v70
	s_nop 0
	v_max3_f32 v210, v210, v71, v72
	s_nop 0
	v_max3_f32 v210, v210, v73, v74
	s_nop 0
	v_max3_f32 v210, v210, v75, v76
	s_nop 0
	v_max3_f32 v210, v210, v77, v78
	s_nop 0
	v_max3_f32 v210, v210, v79, v80
	s_nop 0
	v_max3_f32 v210, v210, v81, v82
	s_nop 0
	v_max3_f32 v210, v210, v83, v83
	s_nop 0
	v_mov_b32_e32 v211, v210
	s_nop 1
	v_permlane32_swap_b32_e32 v210, v211
	v_max_f32_e32 v211, v211, v211
	v_max_f32_e32 v210, v210, v210
	v_max_f32_e32 v210, v210, v211
	v_sub_f32_e32 v236, v210, v237
	v_cmp_lt_f32_e32 vcc, s36, v236
	s_cbranch_vccz .LBB0_941
	v_max_f32_e32 v210, v236, v236
	v_max_f32_e32 v211, 0, v210
	v_exp_f32_e64 v210, -v211
	v_add_f32_e32 v236, v237, v211
	v_pk_mul_f32 v[66:67], v[66:67], v[210:211] op_sel_hi:[1,0]
	v_pk_mul_f32 v[64:65], v[64:65], v[210:211] op_sel_hi:[1,0]
	v_pk_mul_f32 v[62:63], v[62:63], v[210:211] op_sel_hi:[1,0]
	v_pk_mul_f32 v[60:61], v[60:61], v[210:211] op_sel_hi:[1,0]
	v_pk_mul_f32 v[58:59], v[58:59], v[210:211] op_sel_hi:[1,0]
	v_pk_mul_f32 v[56:57], v[56:57], v[210:211] op_sel_hi:[1,0]
	v_pk_mul_f32 v[54:55], v[54:55], v[210:211] op_sel_hi:[1,0]
	v_pk_mul_f32 v[52:53], v[52:53], v[210:211] op_sel_hi:[1,0]
	v_pk_mul_f32 v[50:51], v[50:51], v[210:211] op_sel_hi:[1,0]
	v_pk_mul_f32 v[48:49], v[48:49], v[210:211] op_sel_hi:[1,0]
	v_pk_mul_f32 v[46:47], v[46:47], v[210:211] op_sel_hi:[1,0]
	v_pk_mul_f32 v[44:45], v[44:45], v[210:211] op_sel_hi:[1,0]
	v_pk_mul_f32 v[42:43], v[42:43], v[210:211] op_sel_hi:[1,0]
	v_pk_mul_f32 v[40:41], v[40:41], v[210:211] op_sel_hi:[1,0]
	v_pk_mul_f32 v[38:39], v[38:39], v[210:211] op_sel_hi:[1,0]
	v_pk_mul_f32 v[36:37], v[36:37], v[210:211] op_sel_hi:[1,0]
	v_pk_mul_f32 v[34:35], v[34:35], v[210:211] op_sel_hi:[1,0]
	v_pk_mul_f32 v[32:33], v[32:33], v[210:211] op_sel_hi:[1,0]
	v_pk_mul_f32 v[30:31], v[30:31], v[210:211] op_sel_hi:[1,0]
	v_pk_mul_f32 v[28:29], v[28:29], v[210:211] op_sel_hi:[1,0]
	v_pk_mul_f32 v[26:27], v[26:27], v[210:211] op_sel_hi:[1,0]
	v_pk_mul_f32 v[24:25], v[24:25], v[210:211] op_sel_hi:[1,0]
	v_pk_mul_f32 v[22:23], v[22:23], v[210:211] op_sel_hi:[1,0]
	v_pk_mul_f32 v[20:21], v[20:21], v[210:211] op_sel_hi:[1,0]
	v_pk_mul_f32 v[18:19], v[18:19], v[210:211] op_sel_hi:[1,0]
	v_pk_mul_f32 v[16:17], v[16:17], v[210:211] op_sel_hi:[1,0]
	v_pk_mul_f32 v[14:15], v[14:15], v[210:211] op_sel_hi:[1,0]
	v_pk_mul_f32 v[12:13], v[12:13], v[210:211] op_sel_hi:[1,0]
	v_pk_mul_f32 v[10:11], v[10:11], v[210:211] op_sel_hi:[1,0]
	v_pk_mul_f32 v[8:9], v[8:9], v[210:211] op_sel_hi:[1,0]
	v_pk_mul_f32 v[6:7], v[6:7], v[210:211] op_sel_hi:[1,0]
	v_pk_mul_f32 v[4:5], v[4:5], v[210:211] op_sel_hi:[1,0]
	v_mul_f32_e32 v3, v3, v210
	s_branch .LBB0_942

.LBB0_978:
	s_add_i32 s89, s87, 2
	s_mov_b32 s88, s6
	s_cmp_gt_u32 s87, s83
	s_cbranch_scc1 .LBB0_984
	v_mov_b32_e32 v66, v189
	v_mov_b32_e32 v206, v192
	s_add_i32 s90, s88, 0
	s_cmp_eq_u32 s87, s83
	v_lshlrev_b32_e32 v80, 5, v66
	v_add_u32_e32 v66, s90, v190
	v_add_u32_e32 v66, v66, v80
	ds_read_b128 v[68:71], v66
	ds_read_b128 v[72:75], v66 offset:8192
	v_xad_u32 v67, v80, 32, s90
	v_add_u32_e32 v67, v67, v190
	ds_read_b128 v[76:79], v67
	ds_read_b128 v[98:101], v67 offset:8192
	s_waitcnt lgkmcnt(3)
	v_mfma_f32_32x32x16_bf16 v[114:129], v[68:71], v[138:141], 0
	s_cselect_b64 s[70:71], -1, 0
	s_lshl_b32 s6, s87, 6
	s_sub_i32 s91, 0, s6
	s_cmp_lg_u32 s87, s83
	s_waitcnt lgkmcnt(2)
	v_mfma_f32_32x32x16_bf16 v[82:97], v[72:75], v[138:141], 0
	s_waitcnt lgkmcnt(1)
	v_mfma_f32_32x32x16_bf16 v[114:129], v[76:79], v[142:145], v[114:129]
	v_xad_u32 v68, v80, 64, s90
	v_add_u32_e32 v210, v68, v190
	ds_read_b128 v[68:71], v210
	ds_read_b128 v[72:75], v210 offset:8192
	s_waitcnt lgkmcnt(2)
	v_mfma_f32_32x32x16_bf16 v[82:97], v[98:101], v[142:145], v[82:97]
	v_xor_b32_e32 v76, 0x60, v80
	s_waitcnt lgkmcnt(1)
	v_mfma_f32_32x32x16_bf16 v[114:129], v[68:71], v[154:157], v[114:129]
	v_add_u32_e32 v76, s90, v76
	v_add_u32_e32 v209, v76, v190
	ds_read_b128 v[76:79], v209
	ds_read_b128 v[98:101], v209 offset:8192
	s_waitcnt lgkmcnt(2)
	v_mfma_f32_32x32x16_bf16 v[82:97], v[72:75], v[154:157], v[82:97]
	s_waitcnt lgkmcnt(1)
	v_mfma_f32_32x32x16_bf16 v[114:129], v[76:79], v[158:161], v[114:129]
	v_add_u32_e32 v68, s90, v193
	v_add_u32_e32 v208, v68, v191
	ds_read_b128 v[68:71], v208 offset:16384
	ds_read_b128 v[72:75], v208 offset:18432
	s_waitcnt lgkmcnt(2)
	v_mfma_f32_32x32x16_bf16 v[82:97], v[98:101], v[158:161], v[82:97]
	s_waitcnt lgkmcnt(1)
	v_mfma_f32_32x32x16_bf16 v[114:129], v[68:71], v[170:173], v[114:129]
	v_add_u32_e32 v76, s90, v194
	v_add_u32_e32 v207, v76, v191
	ds_read_b128 v[76:79], v207 offset:16384
	ds_read_b128 v[98:101], v207 offset:18432
	s_waitcnt lgkmcnt(2)
	v_mfma_f32_32x32x16_bf16 v[82:97], v[72:75], v[170:173], v[82:97]
	s_waitcnt lgkmcnt(1)
	v_mfma_f32_32x32x16_bf16 v[114:129], v[76:79], v[174:177], v[114:129]
	s_waitcnt lgkmcnt(0)
	v_mfma_f32_32x32x16_bf16 v[82:97], v[98:101], v[174:177], v[82:97]
	s_cbranch_scc1 .LBB0_981
	v_mov_b32_e32 v68, v1
	s_add_i32 s6, s91, s1
	v_ashrrev_i32_e32 v69, 3, v68
	v_and_b32_e32 v69, -4, v69
	v_and_or_b32 v68, v68, 31, s6
	v_sub_u32_e32 v68, v68, v69
	s_nop 0
	v_cmp_gt_i32_e64 s[66:67], 26, v68
	v_cmp_gt_i32_e64 s[68:69], 27, v68
	v_cmp_gt_i32_e64 s[64:65], 25, v68
	s_and_b64 s[66:67], s[68:69], s[66:67]
	v_cmp_gt_i32_e64 s[62:63], 24, v68
	s_and_b64 s[64:65], s[66:67], s[64:65]
	v_cmp_gt_i32_e64 s[60:61], 19, v68
	s_and_b64 s[62:63], s[64:65], s[62:63]
	v_cmp_gt_i32_e64 s[58:59], 18, v68
	s_and_b64 s[60:61], s[62:63], s[60:61]
	v_cmp_gt_i32_e64 s[56:57], 17, v68
	s_and_b64 s[58:59], s[60:61], s[58:59]
	v_cmp_gt_i32_e64 s[54:55], 16, v68
	s_and_b64 s[56:57], s[58:59], s[56:57]
	v_cmp_gt_i32_e64 s[52:53], 11, v68
	s_and_b64 s[54:55], s[56:57], s[54:55]
	v_cmp_gt_i32_e64 s[50:51], 10, v68
	s_and_b64 s[52:53], s[54:55], s[52:53]
	v_cmp_gt_i32_e64 s[48:49], 9, v68
	s_and_b64 s[50:51], s[52:53], s[50:51]
	v_cmp_gt_i32_e64 s[46:47], 8, v68
	s_and_b64 s[48:49], s[50:51], s[48:49]
	v_cmp_gt_i32_e64 s[44:45], 3, v68
	s_and_b64 s[46:47], s[48:49], s[46:47]
	v_cmp_gt_i32_e64 s[42:43], 2, v68
	s_and_b64 s[44:45], s[46:47], s[44:45]
	v_cmp_gt_i32_e64 s[40:41], 1, v68
	s_and_b64 s[42:43], s[44:45], s[42:43]
	v_cmp_gt_i32_e64 s[36:37], 0, v68
	s_and_b64 s[40:41], s[42:43], s[40:41]
	s_and_b64 s[36:37], s[40:41], s[36:37]
	v_cmp_gt_i32_e64 s[34:35], 58, v68
	v_cndmask_b32_e64 v114, v114, v200, s[36:37]
	v_cmp_gt_i32_e64 s[36:37], 59, v68
	v_cmp_gt_i32_e64 s[30:31], 57, v68
	s_and_b64 s[34:35], s[36:37], s[34:35]
	v_cmp_gt_i32_e64 s[28:29], 56, v68
	s_and_b64 s[30:31], s[34:35], s[30:31]
	v_cmp_gt_i32_e64 s[26:27], 51, v68
	s_and_b64 s[28:29], s[30:31], s[28:29]
	v_cmp_gt_i32_e64 s[24:25], 50, v68
	s_and_b64 s[26:27], s[28:29], s[26:27]
	v_cmp_gt_i32_e64 s[22:23], 49, v68
	s_and_b64 s[24:25], s[26:27], s[24:25]
	v_cmp_gt_i32_e64 s[20:21], 48, v68
	s_and_b64 s[22:23], s[24:25], s[22:23]
	v_cmp_gt_i32_e64 s[18:19], 43, v68
	s_and_b64 s[20:21], s[22:23], s[20:21]
	v_cmp_gt_i32_e64 s[16:17], 42, v68
	s_and_b64 s[18:19], s[20:21], s[18:19]
	v_cmp_gt_i32_e64 s[14:15], 41, v68
	s_and_b64 s[16:17], s[18:19], s[16:17]
	v_cmp_gt_i32_e64 s[12:13], 40, v68
	s_and_b64 s[14:15], s[16:17], s[14:15]
	v_cmp_gt_i32_e64 s[10:11], 35, v68
	s_and_b64 s[12:13], s[14:15], s[12:13]
	v_cmp_gt_i32_e64 s[8:9], 34, v68
	s_and_b64 s[10:11], s[12:13], s[10:11]
	v_cmp_gt_i32_e64 s[6:7], 33, v68
	s_and_b64 s[8:9], s[10:11], s[8:9]
	v_cmp_gt_i32_e32 vcc, 32, v68
	s_and_b64 s[6:7], s[8:9], s[6:7]
	s_and_b64 vcc, s[6:7], vcc
	v_cndmask_b32_e64 v129, v129, v200, s[68:69]
	v_cndmask_b32_e64 v128, v128, v200, s[66:67]
	v_cndmask_b32_e64 v127, v127, v200, s[64:65]
	v_cndmask_b32_e64 v126, v126, v200, s[62:63]
	v_cndmask_b32_e64 v125, v125, v200, s[60:61]
	v_cndmask_b32_e64 v124, v124, v200, s[58:59]
	v_cndmask_b32_e64 v123, v123, v200, s[56:57]
	v_cndmask_b32_e64 v122, v122, v200, s[54:55]
	v_cndmask_b32_e64 v121, v121, v200, s[52:53]
	v_cndmask_b32_e64 v120, v120, v200, s[50:51]
	v_cndmask_b32_e64 v119, v119, v200, s[48:49]
	v_cndmask_b32_e64 v118, v118, v200, s[46:47]
	v_cndmask_b32_e64 v117, v117, v200, s[44:45]
	v_cndmask_b32_e64 v116, v116, v200, s[42:43]
	v_cndmask_b32_e64 v115, v115, v200, s[40:41]
	v_cndmask_b32_e64 v97, v97, v200, s[36:37]
	v_cndmask_b32_e64 v96, v96, v200, s[34:35]
	v_cndmask_b32_e64 v95, v95, v200, s[30:31]
	v_cndmask_b32_e64 v94, v94, v200, s[28:29]
	v_cndmask_b32_e64 v93, v93, v200, s[26:27]
	v_cndmask_b32_e64 v92, v92, v200, s[24:25]
	v_cndmask_b32_e64 v91, v91, v200, s[22:23]
	v_cndmask_b32_e64 v90, v90, v200, s[20:21]
	v_cndmask_b32_e64 v89, v89, v200, s[18:19]
	v_cndmask_b32_e64 v88, v88, v200, s[16:17]
	v_cndmask_b32_e64 v87, v87, v200, s[14:15]
	v_cndmask_b32_e64 v86, v86, v200, s[12:13]
	v_cndmask_b32_e64 v85, v85, v200, s[10:11]
	v_cndmask_b32_e64 v84, v84, v200, s[8:9]
	v_cndmask_b32_e64 v83, v83, v200, s[6:7]
	v_cndmask_b32_e32 v82, v82, v200, vcc

.LBB0_984:
	s_mov_b64 s[6:7], -1

.LBB0_994:
	v_cvt_pk_bf16_f32 v122, v122, v123
	v_cvt_pk_bf16_f32 v123, v124, v125
	v_cvt_pk_bf16_f32 v124, v126, v127
	v_cvt_pk_bf16_f32 v125, v128, v129
	v_sub_f32_e32 v98, v98, v120
	v_sub_f32_e32 v102, v102, v120
	s_waitcnt lgkmcnt(0)
	v_mfma_f32_32x32x16_bf16 v[50:65], v[114:117], v[122:125], v[50:65]
	v_exp_f32_e32 v114, v98
	v_sub_f32_e32 v98, v99, v120
	v_exp_f32_e32 v115, v98
	v_sub_f32_e32 v98, v100, v120
	v_exp_f32_e32 v116, v98
	v_sub_f32_e32 v98, v101, v120
	v_exp_f32_e32 v117, v98
	ds_read_b64_tr_b16 v[126:127], v119 offset:4096
	ds_read_b64_tr_b16 v[128:129], v118 offset:6144
	v_exp_f32_e32 v102, v102
	v_sub_f32_e32 v103, v103, v120
	v_add_f32_e32 v98, 0, v114
	v_exp_f32_e32 v103, v103
	v_add_f32_e32 v98, v115, v98
	v_add_f32_e32 v98, v116, v98
	v_add_f32_e32 v98, v117, v98
	v_add_f32_e32 v203, v203, v207
	v_add_f32_e32 v98, v102, v98
	v_add_f32_e32 v121, v103, v98
	v_cvt_pk_bf16_f32 v82, v82, v83
	v_cvt_pk_bf16_f32 v83, v84, v85
	v_cvt_pk_bf16_f32 v84, v86, v87
	v_sub_f32_e32 v87, v104, v120
	s_waitcnt lgkmcnt(0)
	v_mfma_f32_32x32x16_bf16 v[34:49], v[126:129], v[122:125], v[34:49]
	v_exp_f32_e32 v104, v87
	v_sub_f32_e32 v87, v105, v120
	v_exp_f32_e32 v105, v87
	v_sub_f32_e32 v87, v106, v120
	v_sub_f32_e32 v86, v107, v120
	v_exp_f32_e32 v106, v87
	ds_read_b64_tr_b16 v[98:99], v206 offset:8192
	ds_read_b64_tr_b16 v[100:101], v208 offset:10240
	v_exp_f32_e32 v107, v86
	v_sub_f32_e32 v86, v108, v120
	v_exp_f32_e32 v108, v86
	v_add_f32_e32 v86, v104, v121
	v_add_f32_e32 v86, v105, v86
	v_add_f32_e32 v86, v106, v86
	v_add_f32_e32 v86, v107, v86
	v_cvt_pk_bf16_f32 v85, v88, v89
	v_add_f32_e32 v121, v108, v86
	v_sub_f32_e32 v109, v109, v120
	s_waitcnt lgkmcnt(0)
	v_mfma_f32_32x32x16_bf16 v[50:65], v[98:101], v[82:85], v[50:65]
	v_exp_f32_e32 v109, v109
	v_sub_f32_e32 v98, v110, v120
	v_exp_f32_e32 v110, v98
	v_sub_f32_e32 v98, v111, v120
	v_sub_f32_e32 v112, v112, v120
	v_exp_f32_e32 v111, v98
	ds_read_b64_tr_b16 v[86:87], v119 offset:8192
	ds_read_b64_tr_b16 v[88:89], v118 offset:10240
	v_exp_f32_e32 v112, v112
	v_sub_f32_e32 v113, v113, v120
	v_exp_f32_e32 v113, v113
	v_add_f32_e32 v98, v109, v121
	v_add_f32_e32 v98, v110, v98
	v_add_f32_e32 v98, v111, v98
	v_add_f32_e32 v98, v112, v98
	v_add_f32_e32 v121, v113, v98
	v_sub_f32_e32 v66, v66, v120
	v_exp_f32_e32 v123, v66
	v_sub_f32_e32 v66, v67, v120
	s_waitcnt lgkmcnt(0)
	v_mfma_f32_32x32x16_bf16 v[34:49], v[86:89], v[82:85], v[34:49]
	v_exp_f32_e32 v124, v66
	v_sub_f32_e32 v66, v68, v120
	v_exp_f32_e32 v125, v66
	v_sub_f32_e32 v66, v69, v120
	v_sub_f32_e32 v70, v70, v120
	v_exp_f32_e32 v126, v66
	ds_read_b64_tr_b16 v[98:99], v206 offset:12288
	ds_read_b64_tr_b16 v[100:101], v208 offset:14336
	v_exp_f32_e32 v122, v70
	v_sub_f32_e32 v70, v71, v120
	v_add_f32_e32 v66, v123, v121
	v_exp_f32_e32 v127, v70
	v_add_f32_e32 v66, v124, v66
	v_add_f32_e32 v66, v125, v66
	v_add_f32_e32 v66, v126, v66
	v_add_f32_e32 v66, v122, v66
	v_cvt_pk_bf16_f32 v90, v90, v91
	v_cvt_pk_bf16_f32 v91, v92, v93
	v_cvt_pk_bf16_f32 v92, v94, v95
	v_cvt_pk_bf16_f32 v93, v96, v97
	v_add_f32_e32 v70, v127, v66
	v_sub_f32_e32 v72, v72, v120
	s_waitcnt lgkmcnt(0)
	v_mfma_f32_32x32x16_bf16 v[50:65], v[98:101], v[90:93], v[50:65]
	v_exp_f32_e32 v98, v72
	v_sub_f32_e32 v72, v73, v120
	v_exp_f32_e32 v99, v72
	v_sub_f32_e32 v72, v74, v120
	v_sub_f32_e32 v71, v75, v120
	v_exp_f32_e32 v100, v72
	ds_read_b64_tr_b16 v[66:67], v119 offset:12288
	ds_read_b64_tr_b16 v[68:69], v118 offset:14336
	v_exp_f32_e32 v121, v71
	v_sub_f32_e32 v71, v76, v120
	v_exp_f32_e32 v101, v71
	v_add_f32_e32 v70, v98, v70
	v_add_f32_e32 v70, v99, v70
	v_add_f32_e32 v70, v100, v70
	v_add_f32_e32 v70, v121, v70
	v_add_f32_e32 v70, v101, v70
	v_sub_f32_e32 v72, v77, v120
	v_exp_f32_e32 v129, v72
	v_sub_f32_e32 v72, v78, v120
	s_waitcnt lgkmcnt(0)
	v_mfma_f32_32x32x16_bf16 v[34:49], v[66:69], v[90:93], v[34:49]
	v_sub_f32_e32 v71, v80, v120
	v_exp_f32_e32 v207, v72
	v_sub_f32_e32 v66, v79, v120
	v_exp_f32_e32 v128, v71
	v_sub_f32_e32 v71, v81, v120
	v_exp_f32_e32 v120, v66
	v_exp_f32_e32 v209, v71
	v_add_f32_e32 v66, v129, v70
	v_add_f32_e32 v66, v207, v66
	v_add_f32_e32 v66, v120, v66
	v_add_f32_e32 v66, v128, v66
	v_add_f32_e32 v210, v209, v66
	ds_read_b64_tr_b16 v[70:71], v206
	ds_read_b64_tr_b16 v[72:73], v208 offset:2048
	v_cvt_pk_bf16_f32 v66, v114, v115
	v_cvt_pk_bf16_f32 v67, v116, v117
	v_cvt_pk_bf16_f32 v68, v102, v103
	v_cvt_pk_bf16_f32 v69, v104, v105
	ds_read_b64_tr_b16 v[74:75], v206 offset:4096
	ds_read_b64_tr_b16 v[78:79], v206 offset:8192
	ds_read_b64_tr_b16 v[82:83], v206 offset:12288
	ds_read_b64_tr_b16 v[76:77], v208 offset:6144
	ds_read_b64_tr_b16 v[80:81], v208 offset:10240
	ds_read_b64_tr_b16 v[84:85], v208 offset:14336
	s_waitcnt lgkmcnt(6)
	v_mfma_f32_32x32x16_bf16 v[18:33], v[70:73], v[66:69], v[18:33]
	ds_read_b64_tr_b16 v[72:73], v118 offset:2048
	ds_read_b64_tr_b16 v[70:71], v119
	ds_read_b64_tr_b16 v[86:87], v119 offset:4096
	ds_read_b64_tr_b16 v[90:91], v119 offset:8192
	ds_read_b64_tr_b16 v[94:95], v119 offset:12288
	ds_read_b64_tr_b16 v[88:89], v118 offset:6144
	ds_read_b64_tr_b16 v[92:93], v118 offset:10240
	ds_read_b64_tr_b16 v[96:97], v118 offset:14336
	v_add_f32_e32 v201, v201, v210
	s_waitcnt lgkmcnt(6)
	v_mfma_f32_32x32x16_bf16 v[2:17], v[70:73], v[66:69], v[2:17]
	v_cvt_pk_bf16_f32 v66, v106, v107
	v_cvt_pk_bf16_f32 v67, v108, v109
	v_cvt_pk_bf16_f32 v68, v110, v111
	v_cvt_pk_bf16_f32 v69, v112, v113
	s_nop 1
	v_mfma_f32_32x32x16_bf16 v[18:33], v[74:77], v[66:69], v[18:33]
	s_waitcnt lgkmcnt(2)
	v_mfma_f32_32x32x16_bf16 v[2:17], v[86:89], v[66:69], v[2:17]
	s_waitcnt vmcnt(0)
	s_waitcnt lgkmcnt(0)
	v_mov_b32_e32 v224, s73
	v_mov_b32_e32 v225, 1
	s_mov_b64 s[6:7], exec
	s_mov_b64 exec, s[4:5]
	ds_add_u32 v224, v225
	s_mov_b64 exec, s[6:7]
	v_cvt_pk_bf16_f32 v66, v123, v124
	v_cvt_pk_bf16_f32 v67, v125, v126
	v_cvt_pk_bf16_f32 v68, v122, v127
	v_cvt_pk_bf16_f32 v69, v98, v99
	s_nop 1
	v_mfma_f32_32x32x16_bf16 v[18:33], v[78:81], v[66:69], v[18:33]
	v_mfma_f32_32x32x16_bf16 v[2:17], v[90:93], v[66:69], v[2:17]
	v_cvt_pk_bf16_f32 v66, v100, v121
	v_cvt_pk_bf16_f32 v67, v101, v129
	v_cvt_pk_bf16_f32 v68, v207, v120
	v_cvt_pk_bf16_f32 v69, v128, v209
	s_nop 1
	v_mfma_f32_32x32x16_bf16 v[18:33], v[82:85], v[66:69], v[18:33]
	v_mfma_f32_32x32x16_bf16 v[2:17], v[94:97], v[66:69], v[2:17]
	s_branch .LBB0_1000

.LBB0_1000:
	s_or_b64 exec, exec, s[6:7]
	s_cmp_ge_u32 s89, s82
	s_cbranch_scc1 .Lpr_nodma
	s_mulk_i32 s89, 0x5000
	s_add_u32 s14, s92, s89
	s_addc_u32 s15, s93, 0
	s_add_i32 s16, s33, s85
	s_mov_b32 m0, s16
	s_nop 0
	global_load_lds_dwordx4 v178, s[14:15]
	s_add_i32 s17, s16, 0x1000
	s_mov_b32 m0, s17
	s_add_u32 s18, s14, 0x1400
	s_addc_u32 s19, s15, 0
	global_load_lds_dwordx4 v178, s[18:19]
	s_add_i32 s17, s16, 0x2000
	s_mov_b32 m0, s17
	s_add_u32 s18, s14, 0x2800
	s_addc_u32 s19, s15, 0
	global_load_lds_dwordx4 v178, s[18:19]
	s_add_i32 s17, s16, 0x3000
	s_mov_b32 m0, s17
	s_add_u32 s18, s14, 0x3c00
	s_addc_u32 s19, s15, 0
	global_load_lds_dwordx4 v178, s[18:19]
	s_add_i32 s17, s16, 0x4000
	s_mov_b32 m0, s17
	s_nop 0
	global_load_lds_dwordx4 v202, s[14:15]
.Lpr_nodma:
	v_mov_b32_e32 v66, s73
	ds_read_b32 v66, v66
	s_add_i32 s72, s72, 4
	s_waitcnt lgkmcnt(0)
	v_cmp_le_u32_e32 vcc, s72, v66
	s_cbranch_vccnz .LBB0_1002

.LBB0_1273:
	s_ashr_i32 s39, s38, 31
	s_lshl_b64 s[0:1], s[38:39], 8
	v_lshl_add_u64 v[146:147], s[0:1], 0, v[134:135]
	v_lshl_or_b32 v144, s18, 8, v149
	v_lshlrev_b64 v[154:155], 11, v[146:147]
	v_ashrrev_i32_e32 v145, 31, v144
	v_lshl_add_u64 v[154:155], s[10:11], 0, v[154:155]
	v_lshl_add_u64 v[154:155], v[144:145], 1, v[154:155]
	v_add_co_u32_e32 v224, vcc, 0x8000, v154
	s_nop 1
	v_addc_co_u32_e32 v225, vcc, 0, v155, vcc
	v_add_co_u32_e32 v226, vcc, 0x10000, v154
	s_nop 1
	v_addc_co_u32_e32 v227, vcc, 0, v155, vcc
	v_add_co_u32_e32 v228, vcc, 0x18000, v154
	s_nop 1
	v_addc_co_u32_e32 v229, vcc, 0, v155, vcc
	v_add_co_u32_e32 v230, vcc, 0x40000, v154
	s_nop 1
	v_addc_co_u32_e32 v231, vcc, 0, v155, vcc
	v_add_co_u32_e32 v232, vcc, 0x48000, v154
	s_nop 1
	v_addc_co_u32_e32 v233, vcc, 0, v155, vcc
	v_add_co_u32_e32 v234, vcc, 0x50000, v154
	s_nop 1
	v_addc_co_u32_e32 v235, vcc, 0, v155, vcc
	v_add_co_u32_e32 v214, vcc, 0x58000, v154
	s_nop 1
	v_addc_co_u32_e32 v215, vcc, 0, v155, vcc
	global_load_dwordx2 v[162:163], v[154:155], off
	global_load_dwordx2 v[164:165], v[154:155], off offset:32
	global_load_dwordx2 v[166:167], v[154:155], off offset:256
	global_load_dwordx2 v[168:169], v[154:155], off offset:288
	global_load_dwordx2 v[170:171], v[224:225], off
	global_load_dwordx2 v[172:173], v[224:225], off offset:32
	global_load_dwordx2 v[174:175], v[224:225], off offset:256
	global_load_dwordx2 v[176:177], v[224:225], off offset:288
	global_load_dwordx2 v[178:179], v[226:227], off
	global_load_dwordx2 v[180:181], v[226:227], off offset:32
	global_load_dwordx2 v[182:183], v[226:227], off offset:256
	global_load_dwordx2 v[184:185], v[226:227], off offset:288
	global_load_dwordx2 v[186:187], v[228:229], off
	global_load_dwordx2 v[188:189], v[228:229], off offset:32
	global_load_dwordx2 v[190:191], v[228:229], off offset:256
	global_load_dwordx2 v[192:193], v[228:229], off offset:288
	global_load_dwordx2 v[194:195], v[230:231], off
	global_load_dwordx2 v[196:197], v[230:231], off offset:32
	global_load_dwordx2 v[198:199], v[230:231], off offset:256
	global_load_dwordx2 v[200:201], v[230:231], off offset:288
	global_load_dwordx2 v[202:203], v[232:233], off
	global_load_dwordx2 v[204:205], v[232:233], off offset:32
	global_load_dwordx2 v[206:207], v[232:233], off offset:256
	global_load_dwordx2 v[208:209], v[232:233], off offset:288
	global_load_dwordx2 v[210:211], v[234:235], off
	global_load_dwordx2 v[212:213], v[234:235], off offset:32
	global_load_dwordx2 v[236:237], v[234:235], off offset:256
	global_load_dwordx2 v[238:239], v[234:235], off offset:288
	global_load_dwordx2 v[240:241], v[214:215], off
	global_load_dwordx2 v[242:243], v[214:215], off offset:32
	global_load_dwordx2 v[244:245], v[214:215], off offset:256
	global_load_dwordx2 v[246:247], v[214:215], off offset:288
	v_and_b32_e32 v248, 16, v0
	v_lshrrev_b32_e32 v249, 1, v248
	v_add_u32_e32 v248, v248, v249
	v_mov_b32_e32 v249, 0
	s_waitcnt vmcnt(31)
	v_mov_b32_e32 v156, v162
	v_mov_b32_e32 v157, v163
	s_lshl_b32 s38, s18, 2
	s_ashr_i32 s39, s38, 31
	v_lshlrev_b32_e32 v158, 16, v156
	v_and_b32_e32 v159, 0xffff0000, v156
	v_lshlrev_b32_e32 v156, 16, v157
	v_and_b32_e32 v157, 0xffff0000, v157
	v_pk_add_f32 v[128:129], v[128:129], v[156:157]
	v_pk_add_f32 v[126:127], v[126:127], v[158:159]
	s_nop 0
	v_cvt_pk_bf16_f32 v250, v126, v127
	v_cvt_pk_bf16_f32 v251, v128, v129
	s_waitcnt vmcnt(30)
	v_mov_b32_e32 v158, v164
	v_mov_b32_e32 v159, v165
	v_mul_f32_e32 v127, v127, v127
	v_mul_f32_e32 v129, v129, v129
	v_fmac_f32_e32 v127, v126, v126
	v_fmac_f32_e32 v129, v128, v128
	v_add_f32_e32 v126, v127, v129
	v_lshlrev_b32_e32 v156, 16, v158
	v_and_b32_e32 v157, 0xffff0000, v158
	v_lshlrev_b32_e32 v158, 16, v159
	v_and_b32_e32 v159, 0xffff0000, v159
	v_pk_add_f32 v[124:125], v[124:125], v[158:159]
	v_pk_add_f32 v[122:123], v[122:123], v[156:157]
	s_nop 0
	v_cvt_pk_bf16_f32 v252, v122, v123
	v_cvt_pk_bf16_f32 v253, v124, v125
	s_waitcnt vmcnt(29)
	v_mov_b32_e32 v158, v166
	v_mov_b32_e32 v159, v167
	v_mul_f32_e32 v123, v123, v123
	s_nop 1
	v_permlane16_swap_b32_e32 v250, v252
	v_permlane16_swap_b32_e32 v251, v253
	v_lshl_add_u64 v[220:221], v[154:155], 0, v[248:249]
	global_store_dwordx4 v[220:221], v[250:253], off
	v_mul_f32_e32 v125, v125, v125
	v_fmac_f32_e32 v123, v122, v122
	v_fmac_f32_e32 v125, v124, v124
	v_add_f32_e32 v122, v123, v125
	v_add_f32_e32 v122, v126, v122
	v_lshlrev_b32_e32 v156, 16, v158
	v_and_b32_e32 v157, 0xffff0000, v158
	v_lshlrev_b32_e32 v158, 16, v159
	v_and_b32_e32 v159, 0xffff0000, v159
	v_pk_add_f32 v[120:121], v[120:121], v[158:159]
	v_pk_add_f32 v[156:157], v[118:119], v[156:157]
	v_and_b32_e32 v118, 64, v1
	v_cvt_pk_bf16_f32 v216, v156, v157
	v_cvt_pk_bf16_f32 v217, v120, v121
	s_waitcnt vmcnt(29)
	v_mov_b32_e32 v160, v168
	v_mov_b32_e32 v161, v169
	v_mul_f32_e32 v123, v157, v157
	v_mul_f32_e32 v121, v121, v121
	v_fmac_f32_e32 v123, v156, v156
	v_fmac_f32_e32 v121, v120, v120
	v_add_f32_e32 v120, v123, v121
	v_add_f32_e32 v124, v122, v120
	v_xor_b32_e32 v119, 16, v1
	v_add_u32_e32 v118, 64, v118
	v_cmp_lt_i32_e32 vcc, v119, v118
	v_lshlrev_b32_e32 v120, 16, v160
	v_and_b32_e32 v121, 0xffff0000, v160
	v_lshlrev_b32_e32 v122, 16, v161
	v_and_b32_e32 v123, 0xffff0000, v161
	v_pk_add_f32 v[122:123], v[116:117], v[122:123]
	v_pk_add_f32 v[120:121], v[114:115], v[120:121]
	v_mul_f32_e32 v115, v123, v123
	v_mul_f32_e32 v114, v121, v121
	v_fmac_f32_e32 v114, v120, v120
	v_fmac_f32_e32 v115, v122, v122
	v_cndmask_b32_e32 v119, v1, v119, vcc
	v_add_f32_e32 v114, v114, v115
	v_lshlrev_b32_e32 v119, 2, v119
	v_add_f32_e32 v114, v124, v114
	ds_bpermute_b32 v115, v119, v114
	v_xor_b32_e32 v116, 32, v1
	v_cmp_lt_i32_e32 vcc, v116, v118
	v_cvt_pk_bf16_f32 v218, v120, v121
	v_cvt_pk_bf16_f32 v219, v122, v123
	s_waitcnt lgkmcnt(0)
	v_add_f32_e32 v114, v114, v115
	s_nop 1
	v_permlane16_swap_b32_e32 v216, v218
	v_permlane16_swap_b32_e32 v217, v219
	v_lshl_add_u64 v[220:221], v[154:155], 0, v[248:249]
	global_store_dwordx4 v[220:221], v[216:219], off offset:256
	v_cndmask_b32_e32 v116, v1, v116, vcc
	v_lshlrev_b32_e32 v116, 2, v116
	ds_bpermute_b32 v115, v116, v114
	s_and_saveexec_b64 s[44:45], s[4:5]
	s_cbranch_execz .LBB0_1275
	v_lshlrev_b64 v[120:121], 6, v[146:147]
	v_lshl_add_u64 v[120:121], s[12:13], 0, v[120:121]
	v_lshl_add_u64 v[120:121], s[38:39], 2, v[120:121]
	s_lshl_b32 s18, s57, 2
	v_lshl_add_u64 v[120:121], v[120:121], 0, s[18:19]
	s_waitcnt lgkmcnt(0)
	v_add_f32_e32 v114, v114, v115
	global_store_dword v[120:121], v114, off
.LBB0_1275:
	s_or_b64 exec, exec, s[44:45]
	v_or_b32_e32 v114, 16, v146
	s_waitcnt lgkmcnt(0)
	v_mov_b32_e32 v115, v147
	v_lshlrev_b64 v[120:121], 11, v[114:115]
	v_lshl_add_u64 v[120:121], s[10:11], 0, v[120:121]
	v_lshl_add_u64 v[120:121], v[144:145], 1, v[120:121]
	s_waitcnt vmcnt(29)
	v_mov_b32_e32 v122, v170
	v_mov_b32_e32 v123, v171
	v_lshlrev_b32_e32 v124, 16, v122
	v_and_b32_e32 v125, 0xffff0000, v122
	v_lshlrev_b32_e32 v122, 16, v123
	v_and_b32_e32 v123, 0xffff0000, v123
	v_pk_add_f32 v[112:113], v[112:113], v[122:123]
	v_pk_add_f32 v[110:111], v[110:111], v[124:125]
	s_nop 0
	v_cvt_pk_bf16_f32 v250, v110, v111
	v_cvt_pk_bf16_f32 v251, v112, v113
	s_waitcnt vmcnt(28)
	v_mov_b32_e32 v124, v172
	v_mov_b32_e32 v125, v173
	v_mul_f32_e32 v111, v111, v111
	v_mul_f32_e32 v113, v113, v113
	v_fmac_f32_e32 v111, v110, v110
	v_fmac_f32_e32 v113, v112, v112
	v_add_f32_e32 v110, v111, v113
	v_lshlrev_b32_e32 v122, 16, v124
	v_and_b32_e32 v123, 0xffff0000, v124
	v_lshlrev_b32_e32 v124, 16, v125
	v_and_b32_e32 v125, 0xffff0000, v125
	v_pk_add_f32 v[108:109], v[108:109], v[124:125]
	v_pk_add_f32 v[106:107], v[106:107], v[122:123]
	s_nop 0
	v_cvt_pk_bf16_f32 v252, v106, v107
	v_cvt_pk_bf16_f32 v253, v108, v109
	s_waitcnt vmcnt(27)
	v_mov_b32_e32 v124, v174
	v_mov_b32_e32 v125, v175
	v_mul_f32_e32 v107, v107, v107
	s_nop 1
	v_permlane16_swap_b32_e32 v250, v252
	v_permlane16_swap_b32_e32 v251, v253
	v_lshl_add_u64 v[220:221], v[120:121], 0, v[248:249]
	global_store_dwordx4 v[220:221], v[250:253], off
	v_mul_f32_e32 v109, v109, v109
	v_fmac_f32_e32 v107, v106, v106
	v_fmac_f32_e32 v109, v108, v108
	v_add_f32_e32 v106, v107, v109
	v_add_f32_e32 v106, v110, v106
	v_lshlrev_b32_e32 v122, 16, v124
	v_and_b32_e32 v123, 0xffff0000, v124
	v_lshlrev_b32_e32 v124, 16, v125
	v_and_b32_e32 v125, 0xffff0000, v125
	v_pk_add_f32 v[104:105], v[104:105], v[124:125]
	v_pk_add_f32 v[102:103], v[102:103], v[122:123]
	s_nop 0
	v_cvt_pk_bf16_f32 v216, v102, v103
	v_cvt_pk_bf16_f32 v217, v104, v105
	s_waitcnt vmcnt(27)
	v_mov_b32_e32 v124, v176
	v_mov_b32_e32 v125, v177
	v_mul_f32_e32 v103, v103, v103
	v_mul_f32_e32 v105, v105, v105
	v_fmac_f32_e32 v103, v102, v102
	v_fmac_f32_e32 v105, v104, v104
	v_add_f32_e32 v102, v103, v105
	v_add_f32_e32 v106, v106, v102
	v_lshlrev_b32_e32 v102, 16, v124
	v_and_b32_e32 v103, 0xffff0000, v124
	v_lshlrev_b32_e32 v104, 16, v125
	v_and_b32_e32 v105, 0xffff0000, v125
	v_pk_add_f32 v[100:101], v[100:101], v[104:105]
	v_pk_add_f32 v[102:103], v[98:99], v[102:103]
	v_mul_f32_e32 v99, v101, v101
	v_mul_f32_e32 v98, v103, v103
	v_fmac_f32_e32 v98, v102, v102
	v_fmac_f32_e32 v99, v100, v100
	v_add_f32_e32 v98, v98, v99
	v_add_f32_e32 v98, v106, v98
	ds_bpermute_b32 v99, v119, v98
	v_cvt_pk_bf16_f32 v218, v102, v103
	v_cvt_pk_bf16_f32 v219, v100, v101
	s_nop 1
	v_permlane16_swap_b32_e32 v216, v218
	v_permlane16_swap_b32_e32 v217, v219
	v_lshl_add_u64 v[220:221], v[120:121], 0, v[248:249]
	global_store_dwordx4 v[220:221], v[216:219], off offset:256
	s_waitcnt lgkmcnt(0)
	v_add_f32_e32 v98, v98, v99
	ds_bpermute_b32 v99, v116, v98
	s_and_saveexec_b64 s[44:45], s[4:5]
	s_cbranch_execz .LBB0_1277
	v_lshlrev_b64 v[100:101], 6, v[114:115]
	v_lshl_add_u64 v[100:101], s[12:13], 0, v[100:101]
	v_lshl_add_u64 v[100:101], s[38:39], 2, v[100:101]
	s_lshl_b32 s18, s57, 2
	v_lshl_add_u64 v[100:101], v[100:101], 0, s[18:19]
	s_waitcnt lgkmcnt(0)
	v_add_f32_e32 v98, v98, v99
	global_store_dword v[100:101], v98, off
.LBB0_1277:
	s_or_b64 exec, exec, s[44:45]
	v_or_b32_e32 v98, 32, v146
	s_waitcnt lgkmcnt(0)
	v_mov_b32_e32 v99, v147
	v_lshlrev_b64 v[100:101], 11, v[98:99]
	v_lshl_add_u64 v[100:101], s[10:11], 0, v[100:101]
	v_lshl_add_u64 v[100:101], v[144:145], 1, v[100:101]
	s_waitcnt vmcnt(27)
	v_mov_b32_e32 v102, v178
	v_mov_b32_e32 v103, v179
	v_lshlrev_b32_e32 v104, 16, v102
	v_and_b32_e32 v105, 0xffff0000, v102
	v_lshlrev_b32_e32 v102, 16, v103
	v_and_b32_e32 v103, 0xffff0000, v103
	v_pk_add_f32 v[96:97], v[96:97], v[102:103]
	v_pk_add_f32 v[94:95], v[94:95], v[104:105]
	s_nop 0
	v_cvt_pk_bf16_f32 v250, v94, v95
	v_cvt_pk_bf16_f32 v251, v96, v97
	s_waitcnt vmcnt(26)
	v_mov_b32_e32 v104, v180
	v_mov_b32_e32 v105, v181
	v_mul_f32_e32 v95, v95, v95
	v_mul_f32_e32 v97, v97, v97
	v_fmac_f32_e32 v95, v94, v94
	v_fmac_f32_e32 v97, v96, v96
	v_add_f32_e32 v94, v95, v97
	v_lshlrev_b32_e32 v102, 16, v104
	v_and_b32_e32 v103, 0xffff0000, v104
	v_lshlrev_b32_e32 v104, 16, v105
	v_and_b32_e32 v105, 0xffff0000, v105
	v_pk_add_f32 v[92:93], v[92:93], v[104:105]
	v_pk_add_f32 v[90:91], v[90:91], v[102:103]
	s_nop 0
	v_cvt_pk_bf16_f32 v252, v90, v91
	v_cvt_pk_bf16_f32 v253, v92, v93
	s_waitcnt vmcnt(25)
	v_mov_b32_e32 v104, v182
	v_mov_b32_e32 v105, v183
	v_mul_f32_e32 v91, v91, v91
	s_nop 1
	v_permlane16_swap_b32_e32 v250, v252
	v_permlane16_swap_b32_e32 v251, v253
	v_lshl_add_u64 v[220:221], v[100:101], 0, v[248:249]
	global_store_dwordx4 v[220:221], v[250:253], off
	v_mul_f32_e32 v93, v93, v93
	v_fmac_f32_e32 v91, v90, v90
	v_fmac_f32_e32 v93, v92, v92
	v_add_f32_e32 v90, v91, v93
	v_add_f32_e32 v90, v94, v90
	v_lshlrev_b32_e32 v102, 16, v104
	v_and_b32_e32 v103, 0xffff0000, v104
	v_lshlrev_b32_e32 v104, 16, v105
	v_and_b32_e32 v105, 0xffff0000, v105
	v_pk_add_f32 v[88:89], v[88:89], v[104:105]
	v_pk_add_f32 v[86:87], v[86:87], v[102:103]
	s_nop 0
	v_cvt_pk_bf16_f32 v216, v86, v87
	v_cvt_pk_bf16_f32 v217, v88, v89
	s_waitcnt vmcnt(25)
	v_mov_b32_e32 v104, v184
	v_mov_b32_e32 v105, v185
	v_mul_f32_e32 v87, v87, v87
	v_mul_f32_e32 v89, v89, v89
	v_fmac_f32_e32 v87, v86, v86
	v_fmac_f32_e32 v89, v88, v88
	v_add_f32_e32 v86, v87, v89
	v_add_f32_e32 v90, v90, v86
	v_lshlrev_b32_e32 v86, 16, v104
	v_and_b32_e32 v87, 0xffff0000, v104
	v_lshlrev_b32_e32 v88, 16, v105
	v_and_b32_e32 v89, 0xffff0000, v105
	v_pk_add_f32 v[84:85], v[84:85], v[88:89]
	v_pk_add_f32 v[86:87], v[82:83], v[86:87]
	v_mul_f32_e32 v83, v85, v85
	v_mul_f32_e32 v82, v87, v87
	v_fmac_f32_e32 v82, v86, v86
	v_fmac_f32_e32 v83, v84, v84
	v_add_f32_e32 v82, v82, v83
	v_add_f32_e32 v82, v90, v82
	ds_bpermute_b32 v83, v119, v82
	v_cvt_pk_bf16_f32 v218, v86, v87
	v_cvt_pk_bf16_f32 v219, v84, v85
	s_nop 1
	v_permlane16_swap_b32_e32 v216, v218
	v_permlane16_swap_b32_e32 v217, v219
	v_lshl_add_u64 v[220:221], v[100:101], 0, v[248:249]
	global_store_dwordx4 v[220:221], v[216:219], off offset:256
	s_waitcnt lgkmcnt(0)
	v_add_f32_e32 v82, v82, v83
	ds_bpermute_b32 v83, v116, v82
	s_and_saveexec_b64 s[44:45], s[4:5]
	s_cbranch_execz .LBB0_1279
	v_lshlrev_b64 v[84:85], 6, v[98:99]
	v_lshl_add_u64 v[84:85], s[12:13], 0, v[84:85]
	v_lshl_add_u64 v[84:85], s[38:39], 2, v[84:85]
	s_lshl_b32 s18, s57, 2
	v_lshl_add_u64 v[84:85], v[84:85], 0, s[18:19]
	s_waitcnt lgkmcnt(0)
	v_add_f32_e32 v82, v82, v83
	global_store_dword v[84:85], v82, off
.LBB0_1279:
	s_or_b64 exec, exec, s[44:45]
	v_or_b32_e32 v82, 48, v146
	s_waitcnt lgkmcnt(0)
	v_mov_b32_e32 v83, v147
	v_lshlrev_b64 v[84:85], 11, v[82:83]
	v_lshl_add_u64 v[84:85], s[10:11], 0, v[84:85]
	v_lshl_add_u64 v[84:85], v[144:145], 1, v[84:85]
	s_waitcnt vmcnt(25)
	v_mov_b32_e32 v86, v186
	v_mov_b32_e32 v87, v187
	v_lshlrev_b32_e32 v88, 16, v86
	v_and_b32_e32 v89, 0xffff0000, v86
	v_lshlrev_b32_e32 v86, 16, v87
	v_and_b32_e32 v87, 0xffff0000, v87
	v_pk_add_f32 v[80:81], v[80:81], v[86:87]
	v_pk_add_f32 v[78:79], v[78:79], v[88:89]
	s_nop 0
	v_cvt_pk_bf16_f32 v250, v78, v79
	v_cvt_pk_bf16_f32 v251, v80, v81
	s_waitcnt vmcnt(24)
	v_mov_b32_e32 v88, v188
	v_mov_b32_e32 v89, v189
	v_mul_f32_e32 v79, v79, v79
	v_mul_f32_e32 v81, v81, v81
	v_fmac_f32_e32 v79, v78, v78
	v_fmac_f32_e32 v81, v80, v80
	v_add_f32_e32 v78, v79, v81
	v_lshlrev_b32_e32 v86, 16, v88
	v_and_b32_e32 v87, 0xffff0000, v88
	v_lshlrev_b32_e32 v88, 16, v89
	v_and_b32_e32 v89, 0xffff0000, v89
	v_pk_add_f32 v[76:77], v[76:77], v[88:89]
	v_pk_add_f32 v[74:75], v[74:75], v[86:87]
	s_nop 0
	v_cvt_pk_bf16_f32 v252, v74, v75
	v_cvt_pk_bf16_f32 v253, v76, v77
	s_waitcnt vmcnt(23)
	v_mov_b32_e32 v88, v190
	v_mov_b32_e32 v89, v191
	v_mul_f32_e32 v75, v75, v75
	s_nop 1
	v_permlane16_swap_b32_e32 v250, v252
	v_permlane16_swap_b32_e32 v251, v253
	v_lshl_add_u64 v[220:221], v[84:85], 0, v[248:249]
	global_store_dwordx4 v[220:221], v[250:253], off
	v_mul_f32_e32 v77, v77, v77
	v_fmac_f32_e32 v75, v74, v74
	v_fmac_f32_e32 v77, v76, v76
	v_add_f32_e32 v74, v75, v77
	v_add_f32_e32 v74, v78, v74
	v_lshlrev_b32_e32 v86, 16, v88
	v_and_b32_e32 v87, 0xffff0000, v88
	v_lshlrev_b32_e32 v88, 16, v89
	v_and_b32_e32 v89, 0xffff0000, v89
	v_pk_add_f32 v[72:73], v[72:73], v[88:89]
	v_pk_add_f32 v[70:71], v[70:71], v[86:87]
	s_nop 0
	v_cvt_pk_bf16_f32 v216, v70, v71
	v_cvt_pk_bf16_f32 v217, v72, v73
	s_waitcnt vmcnt(23)
	v_mov_b32_e32 v88, v192
	v_mov_b32_e32 v89, v193
	v_mul_f32_e32 v71, v71, v71
	v_mul_f32_e32 v73, v73, v73
	v_fmac_f32_e32 v71, v70, v70
	v_fmac_f32_e32 v73, v72, v72
	v_add_f32_e32 v70, v71, v73
	v_add_f32_e32 v74, v74, v70
	v_lshlrev_b32_e32 v70, 16, v88
	v_and_b32_e32 v71, 0xffff0000, v88
	v_lshlrev_b32_e32 v72, 16, v89
	v_and_b32_e32 v73, 0xffff0000, v89
	v_pk_add_f32 v[68:69], v[68:69], v[72:73]
	v_pk_add_f32 v[70:71], v[66:67], v[70:71]
	v_mul_f32_e32 v67, v69, v69
	v_mul_f32_e32 v66, v71, v71
	v_fmac_f32_e32 v66, v70, v70
	v_fmac_f32_e32 v67, v68, v68
	v_add_f32_e32 v66, v66, v67
	v_add_f32_e32 v66, v74, v66
	ds_bpermute_b32 v67, v119, v66
	v_cvt_pk_bf16_f32 v218, v70, v71
	v_cvt_pk_bf16_f32 v219, v68, v69
	s_nop 1
	v_permlane16_swap_b32_e32 v216, v218
	v_permlane16_swap_b32_e32 v217, v219
	v_lshl_add_u64 v[220:221], v[84:85], 0, v[248:249]
	global_store_dwordx4 v[220:221], v[216:219], off offset:256
	s_waitcnt lgkmcnt(0)
	v_add_f32_e32 v66, v66, v67
	ds_bpermute_b32 v67, v116, v66
	s_and_saveexec_b64 s[44:45], s[4:5]
	s_cbranch_execz .LBB0_1281
	v_lshlrev_b64 v[68:69], 6, v[82:83]
	v_lshl_add_u64 v[68:69], s[12:13], 0, v[68:69]
	v_lshl_add_u64 v[68:69], s[38:39], 2, v[68:69]
	s_lshl_b32 s18, s57, 2
	v_lshl_add_u64 v[68:69], v[68:69], 0, s[18:19]
	s_waitcnt lgkmcnt(0)
	v_add_f32_e32 v66, v66, v67
	global_store_dword v[68:69], v66, off
.LBB0_1281:
	s_or_b64 exec, exec, s[44:45]
	s_waitcnt lgkmcnt(0)
	v_lshl_add_u64 v[66:67], v[146:147], 0, s[22:23]
	v_lshlrev_b64 v[68:69], 11, v[66:67]
	v_lshl_add_u64 v[68:69], s[10:11], 0, v[68:69]
	v_lshl_add_u64 v[68:69], v[144:145], 1, v[68:69]
	s_waitcnt vmcnt(23)
	v_mov_b32_e32 v70, v194
	v_mov_b32_e32 v71, v195
	v_lshlrev_b32_e32 v72, 16, v70
	v_and_b32_e32 v73, 0xffff0000, v70
	v_lshlrev_b32_e32 v70, 16, v71
	v_and_b32_e32 v71, 0xffff0000, v71
	v_pk_add_f32 v[64:65], v[64:65], v[70:71]
	v_pk_add_f32 v[62:63], v[62:63], v[72:73]
	s_nop 0
	v_cvt_pk_bf16_f32 v250, v62, v63
	v_cvt_pk_bf16_f32 v251, v64, v65
	s_waitcnt vmcnt(22)
	v_mov_b32_e32 v72, v196
	v_mov_b32_e32 v73, v197
	v_mul_f32_e32 v63, v63, v63
	v_mul_f32_e32 v65, v65, v65
	v_fmac_f32_e32 v63, v62, v62
	v_fmac_f32_e32 v65, v64, v64
	v_add_f32_e32 v62, v63, v65
	v_lshlrev_b32_e32 v70, 16, v72
	v_and_b32_e32 v71, 0xffff0000, v72
	v_lshlrev_b32_e32 v72, 16, v73
	v_and_b32_e32 v73, 0xffff0000, v73
	v_pk_add_f32 v[60:61], v[60:61], v[72:73]
	v_pk_add_f32 v[58:59], v[58:59], v[70:71]
	s_nop 0
	v_cvt_pk_bf16_f32 v252, v58, v59
	v_cvt_pk_bf16_f32 v253, v60, v61
	s_waitcnt vmcnt(21)
	v_mov_b32_e32 v72, v198
	v_mov_b32_e32 v73, v199
	v_mul_f32_e32 v59, v59, v59
	s_nop 1
	v_permlane16_swap_b32_e32 v250, v252
	v_permlane16_swap_b32_e32 v251, v253
	v_lshl_add_u64 v[220:221], v[68:69], 0, v[248:249]
	global_store_dwordx4 v[220:221], v[250:253], off
	v_mul_f32_e32 v61, v61, v61
	v_fmac_f32_e32 v59, v58, v58
	v_fmac_f32_e32 v61, v60, v60
	v_add_f32_e32 v58, v59, v61
	v_add_f32_e32 v58, v62, v58
	v_lshlrev_b32_e32 v70, 16, v72
	v_and_b32_e32 v71, 0xffff0000, v72
	v_lshlrev_b32_e32 v72, 16, v73
	v_and_b32_e32 v73, 0xffff0000, v73
	v_pk_add_f32 v[56:57], v[56:57], v[72:73]
	v_pk_add_f32 v[54:55], v[54:55], v[70:71]
	s_nop 0
	v_cvt_pk_bf16_f32 v216, v54, v55
	v_cvt_pk_bf16_f32 v217, v56, v57
	s_waitcnt vmcnt(21)
	v_mov_b32_e32 v72, v200
	v_mov_b32_e32 v73, v201
	v_mul_f32_e32 v55, v55, v55
	v_mul_f32_e32 v57, v57, v57
	v_fmac_f32_e32 v55, v54, v54
	v_fmac_f32_e32 v57, v56, v56
	v_add_f32_e32 v54, v55, v57
	v_add_f32_e32 v58, v58, v54
	v_lshlrev_b32_e32 v54, 16, v72
	v_and_b32_e32 v55, 0xffff0000, v72
	v_lshlrev_b32_e32 v56, 16, v73
	v_and_b32_e32 v57, 0xffff0000, v73
	v_pk_add_f32 v[52:53], v[52:53], v[56:57]
	v_pk_add_f32 v[54:55], v[50:51], v[54:55]
	v_mul_f32_e32 v51, v53, v53
	v_mul_f32_e32 v50, v55, v55
	v_fmac_f32_e32 v50, v54, v54
	v_fmac_f32_e32 v51, v52, v52
	v_add_f32_e32 v50, v50, v51
	v_add_f32_e32 v50, v58, v50
	ds_bpermute_b32 v51, v119, v50
	v_cvt_pk_bf16_f32 v218, v54, v55
	v_cvt_pk_bf16_f32 v219, v52, v53
	s_nop 1
	v_permlane16_swap_b32_e32 v216, v218
	v_permlane16_swap_b32_e32 v217, v219
	v_lshl_add_u64 v[220:221], v[68:69], 0, v[248:249]
	global_store_dwordx4 v[220:221], v[216:219], off offset:256
	s_waitcnt lgkmcnt(0)
	v_add_f32_e32 v50, v50, v51
	ds_bpermute_b32 v51, v116, v50
	s_and_saveexec_b64 s[44:45], s[4:5]
	s_cbranch_execz .LBB0_1283
	v_lshlrev_b64 v[52:53], 6, v[66:67]
	v_lshl_add_u64 v[52:53], s[12:13], 0, v[52:53]
	v_lshl_add_u64 v[52:53], s[38:39], 2, v[52:53]
	s_lshl_b32 s18, s57, 2
	v_lshl_add_u64 v[52:53], v[52:53], 0, s[18:19]
	s_waitcnt lgkmcnt(0)
	v_add_f32_e32 v50, v50, v51
	global_store_dword v[52:53], v50, off
.LBB0_1283:
	s_or_b64 exec, exec, s[44:45]
	s_waitcnt lgkmcnt(0)
	v_lshl_add_u64 v[50:51], v[146:147], 0, s[26:27]
	v_lshlrev_b64 v[52:53], 11, v[50:51]
	v_lshl_add_u64 v[52:53], s[10:11], 0, v[52:53]
	v_lshl_add_u64 v[52:53], v[144:145], 1, v[52:53]
	s_waitcnt vmcnt(21)
	v_mov_b32_e32 v54, v202
	v_mov_b32_e32 v55, v203
	v_lshlrev_b32_e32 v56, 16, v54
	v_and_b32_e32 v57, 0xffff0000, v54
	v_lshlrev_b32_e32 v54, 16, v55
	v_and_b32_e32 v55, 0xffff0000, v55
	v_pk_add_f32 v[48:49], v[48:49], v[54:55]
	v_pk_add_f32 v[46:47], v[46:47], v[56:57]
	s_nop 0
	v_cvt_pk_bf16_f32 v250, v46, v47
	v_cvt_pk_bf16_f32 v251, v48, v49
	s_waitcnt vmcnt(20)
	v_mov_b32_e32 v56, v204
	v_mov_b32_e32 v57, v205
	v_mul_f32_e32 v47, v47, v47
	v_mul_f32_e32 v49, v49, v49
	v_fmac_f32_e32 v47, v46, v46
	v_fmac_f32_e32 v49, v48, v48
	v_add_f32_e32 v46, v47, v49
	v_lshlrev_b32_e32 v54, 16, v56
	v_and_b32_e32 v55, 0xffff0000, v56
	v_lshlrev_b32_e32 v56, 16, v57
	v_and_b32_e32 v57, 0xffff0000, v57
	v_pk_add_f32 v[44:45], v[44:45], v[56:57]
	v_pk_add_f32 v[42:43], v[42:43], v[54:55]
	s_nop 0
	v_cvt_pk_bf16_f32 v252, v42, v43
	v_cvt_pk_bf16_f32 v253, v44, v45
	s_waitcnt vmcnt(19)
	v_mov_b32_e32 v56, v206
	v_mov_b32_e32 v57, v207
	v_mul_f32_e32 v43, v43, v43
	s_nop 1
	v_permlane16_swap_b32_e32 v250, v252
	v_permlane16_swap_b32_e32 v251, v253
	v_lshl_add_u64 v[220:221], v[52:53], 0, v[248:249]
	global_store_dwordx4 v[220:221], v[250:253], off
	v_mul_f32_e32 v45, v45, v45
	v_fmac_f32_e32 v43, v42, v42
	v_fmac_f32_e32 v45, v44, v44
	v_add_f32_e32 v42, v43, v45
	v_add_f32_e32 v42, v46, v42
	v_lshlrev_b32_e32 v54, 16, v56
	v_and_b32_e32 v55, 0xffff0000, v56
	v_lshlrev_b32_e32 v56, 16, v57
	v_and_b32_e32 v57, 0xffff0000, v57
	v_pk_add_f32 v[40:41], v[40:41], v[56:57]
	v_pk_add_f32 v[38:39], v[38:39], v[54:55]
	s_nop 0
	v_cvt_pk_bf16_f32 v216, v38, v39
	v_cvt_pk_bf16_f32 v217, v40, v41
	s_waitcnt vmcnt(19)
	v_mov_b32_e32 v56, v208
	v_mov_b32_e32 v57, v209
	v_mul_f32_e32 v39, v39, v39
	v_mul_f32_e32 v41, v41, v41
	v_fmac_f32_e32 v39, v38, v38
	v_fmac_f32_e32 v41, v40, v40
	v_add_f32_e32 v38, v39, v41
	v_add_f32_e32 v42, v42, v38
	v_lshlrev_b32_e32 v38, 16, v56
	v_and_b32_e32 v39, 0xffff0000, v56
	v_lshlrev_b32_e32 v40, 16, v57
	v_and_b32_e32 v41, 0xffff0000, v57
	v_pk_add_f32 v[36:37], v[36:37], v[40:41]
	v_pk_add_f32 v[38:39], v[34:35], v[38:39]
	v_mul_f32_e32 v35, v37, v37
	v_mul_f32_e32 v34, v39, v39
	v_fmac_f32_e32 v34, v38, v38
	v_fmac_f32_e32 v35, v36, v36
	v_add_f32_e32 v34, v34, v35
	v_add_f32_e32 v34, v42, v34
	ds_bpermute_b32 v35, v119, v34
	v_cvt_pk_bf16_f32 v218, v38, v39
	v_cvt_pk_bf16_f32 v219, v36, v37
	s_nop 1
	v_permlane16_swap_b32_e32 v216, v218
	v_permlane16_swap_b32_e32 v217, v219
	v_lshl_add_u64 v[220:221], v[52:53], 0, v[248:249]
	global_store_dwordx4 v[220:221], v[216:219], off offset:256
	s_waitcnt lgkmcnt(0)
	v_add_f32_e32 v34, v34, v35
	ds_bpermute_b32 v35, v116, v34
	s_and_saveexec_b64 s[44:45], s[4:5]
	s_cbranch_execz .LBB0_1285
	v_lshlrev_b64 v[36:37], 6, v[50:51]
	v_lshl_add_u64 v[36:37], s[12:13], 0, v[36:37]
	v_lshl_add_u64 v[36:37], s[38:39], 2, v[36:37]
	s_lshl_b32 s18, s57, 2
	v_lshl_add_u64 v[36:37], v[36:37], 0, s[18:19]
	s_waitcnt lgkmcnt(0)
	v_add_f32_e32 v34, v34, v35
	global_store_dword v[36:37], v34, off
.LBB0_1285:
	s_or_b64 exec, exec, s[44:45]
	s_waitcnt lgkmcnt(0)
	v_lshl_add_u64 v[34:35], v[146:147], 0, s[28:29]
	v_lshlrev_b64 v[36:37], 11, v[34:35]
	v_lshl_add_u64 v[36:37], s[10:11], 0, v[36:37]
	v_lshl_add_u64 v[36:37], v[144:145], 1, v[36:37]
	s_waitcnt vmcnt(19)
	v_mov_b32_e32 v38, v210
	v_mov_b32_e32 v39, v211
	v_lshlrev_b32_e32 v40, 16, v38
	v_and_b32_e32 v41, 0xffff0000, v38
	v_lshlrev_b32_e32 v38, 16, v39
	v_and_b32_e32 v39, 0xffff0000, v39
	v_pk_add_f32 v[32:33], v[32:33], v[38:39]
	v_pk_add_f32 v[30:31], v[30:31], v[40:41]
	s_nop 0
	v_cvt_pk_bf16_f32 v250, v30, v31
	v_cvt_pk_bf16_f32 v251, v32, v33
	s_waitcnt vmcnt(18)
	v_mov_b32_e32 v40, v212
	v_mov_b32_e32 v41, v213
	v_mul_f32_e32 v31, v31, v31
	v_mul_f32_e32 v33, v33, v33
	v_fmac_f32_e32 v31, v30, v30
	v_fmac_f32_e32 v33, v32, v32
	v_add_f32_e32 v30, v31, v33
	v_lshlrev_b32_e32 v38, 16, v40
	v_and_b32_e32 v39, 0xffff0000, v40
	v_lshlrev_b32_e32 v40, 16, v41
	v_and_b32_e32 v41, 0xffff0000, v41
	v_pk_add_f32 v[28:29], v[28:29], v[40:41]
	v_pk_add_f32 v[26:27], v[26:27], v[38:39]
	s_nop 0
	v_cvt_pk_bf16_f32 v252, v26, v27
	v_cvt_pk_bf16_f32 v253, v28, v29
	s_waitcnt vmcnt(17)
	v_mov_b32_e32 v40, v236
	v_mov_b32_e32 v41, v237
	v_mul_f32_e32 v27, v27, v27
	s_nop 1
	v_permlane16_swap_b32_e32 v250, v252
	v_permlane16_swap_b32_e32 v251, v253
	v_lshl_add_u64 v[220:221], v[36:37], 0, v[248:249]
	global_store_dwordx4 v[220:221], v[250:253], off
	v_mul_f32_e32 v29, v29, v29
	v_fmac_f32_e32 v27, v26, v26
	v_fmac_f32_e32 v29, v28, v28
	v_add_f32_e32 v26, v27, v29
	v_add_f32_e32 v26, v30, v26
	v_lshlrev_b32_e32 v38, 16, v40
	v_and_b32_e32 v39, 0xffff0000, v40
	v_lshlrev_b32_e32 v40, 16, v41
	v_and_b32_e32 v41, 0xffff0000, v41
	v_pk_add_f32 v[24:25], v[24:25], v[40:41]
	v_pk_add_f32 v[22:23], v[22:23], v[38:39]
	s_nop 0
	v_cvt_pk_bf16_f32 v216, v22, v23
	v_cvt_pk_bf16_f32 v217, v24, v25
	s_waitcnt vmcnt(17)
	v_mov_b32_e32 v40, v238
	v_mov_b32_e32 v41, v239
	v_mul_f32_e32 v23, v23, v23
	v_mul_f32_e32 v25, v25, v25
	v_fmac_f32_e32 v23, v22, v22
	v_fmac_f32_e32 v25, v24, v24
	v_add_f32_e32 v22, v23, v25
	v_add_f32_e32 v26, v26, v22
	v_lshlrev_b32_e32 v22, 16, v40
	v_and_b32_e32 v23, 0xffff0000, v40
	v_lshlrev_b32_e32 v24, 16, v41
	v_and_b32_e32 v25, 0xffff0000, v41
	v_pk_add_f32 v[20:21], v[20:21], v[24:25]
	v_pk_add_f32 v[22:23], v[18:19], v[22:23]
	v_mul_f32_e32 v19, v21, v21
	v_mul_f32_e32 v18, v23, v23
	v_fmac_f32_e32 v18, v22, v22
	v_fmac_f32_e32 v19, v20, v20
	v_add_f32_e32 v18, v18, v19
	v_add_f32_e32 v18, v26, v18
	ds_bpermute_b32 v19, v119, v18
	v_cvt_pk_bf16_f32 v218, v22, v23
	v_cvt_pk_bf16_f32 v219, v20, v21
	s_nop 1
	v_permlane16_swap_b32_e32 v216, v218
	v_permlane16_swap_b32_e32 v217, v219
	v_lshl_add_u64 v[220:221], v[36:37], 0, v[248:249]
	global_store_dwordx4 v[220:221], v[216:219], off offset:256
	s_waitcnt lgkmcnt(0)
	v_add_f32_e32 v18, v18, v19
	ds_bpermute_b32 v19, v116, v18
	s_and_saveexec_b64 s[44:45], s[4:5]
	s_cbranch_execz .LBB0_1287
	v_lshlrev_b64 v[20:21], 6, v[34:35]
	v_lshl_add_u64 v[20:21], s[12:13], 0, v[20:21]
	v_lshl_add_u64 v[20:21], s[38:39], 2, v[20:21]
	s_lshl_b32 s18, s57, 2
	v_lshl_add_u64 v[20:21], v[20:21], 0, s[18:19]
	s_waitcnt lgkmcnt(0)
	v_add_f32_e32 v18, v18, v19
	global_store_dword v[20:21], v18, off
.LBB0_1287:
	s_or_b64 exec, exec, s[44:45]
	s_waitcnt lgkmcnt(0)
	v_lshl_add_u64 v[18:19], v[146:147], 0, s[30:31]
	v_lshlrev_b64 v[20:21], 11, v[18:19]
	v_lshl_add_u64 v[20:21], s[10:11], 0, v[20:21]
	v_lshl_add_u64 v[20:21], v[144:145], 1, v[20:21]
	s_waitcnt vmcnt(17)
	v_mov_b32_e32 v22, v240
	v_mov_b32_e32 v23, v241
	v_lshlrev_b32_e32 v24, 16, v22
	v_and_b32_e32 v25, 0xffff0000, v22
	v_lshlrev_b32_e32 v22, 16, v23
	v_and_b32_e32 v23, 0xffff0000, v23
	v_pk_add_f32 v[16:17], v[16:17], v[22:23]
	v_pk_add_f32 v[14:15], v[14:15], v[24:25]
	s_nop 0
	v_cvt_pk_bf16_f32 v250, v14, v15
	v_cvt_pk_bf16_f32 v251, v16, v17
	s_waitcnt vmcnt(16)
	v_mov_b32_e32 v24, v242
	v_mov_b32_e32 v25, v243
	v_mul_f32_e32 v15, v15, v15
	v_mul_f32_e32 v17, v17, v17
	v_fmac_f32_e32 v15, v14, v14
	v_fmac_f32_e32 v17, v16, v16
	v_add_f32_e32 v14, v15, v17
	v_lshlrev_b32_e32 v22, 16, v24
	v_and_b32_e32 v23, 0xffff0000, v24
	v_lshlrev_b32_e32 v24, 16, v25
	v_and_b32_e32 v25, 0xffff0000, v25
	v_pk_add_f32 v[12:13], v[12:13], v[24:25]
	v_pk_add_f32 v[10:11], v[10:11], v[22:23]
	s_nop 0
	v_cvt_pk_bf16_f32 v252, v10, v11
	v_cvt_pk_bf16_f32 v253, v12, v13
	s_waitcnt vmcnt(15)
	v_mov_b32_e32 v24, v244
	v_mov_b32_e32 v25, v245
	v_mul_f32_e32 v11, v11, v11
	s_nop 1
	v_permlane16_swap_b32_e32 v250, v252
	v_permlane16_swap_b32_e32 v251, v253
	v_lshl_add_u64 v[220:221], v[20:21], 0, v[248:249]
	global_store_dwordx4 v[220:221], v[250:253], off
	v_mul_f32_e32 v13, v13, v13
	v_fmac_f32_e32 v11, v10, v10
	v_fmac_f32_e32 v13, v12, v12
	v_add_f32_e32 v10, v11, v13
	v_add_f32_e32 v10, v14, v10
	v_lshlrev_b32_e32 v22, 16, v24
	v_and_b32_e32 v23, 0xffff0000, v24
	v_lshlrev_b32_e32 v24, 16, v25
	v_and_b32_e32 v25, 0xffff0000, v25
	v_pk_add_f32 v[8:9], v[8:9], v[24:25]
	v_pk_add_f32 v[6:7], v[6:7], v[22:23]
	s_nop 0
	v_cvt_pk_bf16_f32 v216, v6, v7
	v_cvt_pk_bf16_f32 v217, v8, v9
	s_waitcnt vmcnt(15)
	v_mov_b32_e32 v24, v246
	v_mov_b32_e32 v25, v247
	v_mul_f32_e32 v7, v7, v7
	v_mul_f32_e32 v9, v9, v9
	v_fmac_f32_e32 v7, v6, v6
	v_fmac_f32_e32 v9, v8, v8
	v_add_f32_e32 v6, v7, v9
	v_add_f32_e32 v10, v10, v6
	v_lshlrev_b32_e32 v6, 16, v24
	v_and_b32_e32 v7, 0xffff0000, v24
	v_lshlrev_b32_e32 v8, 16, v25
	v_and_b32_e32 v9, 0xffff0000, v25
	v_pk_add_f32 v[4:5], v[4:5], v[8:9]
	v_pk_add_f32 v[6:7], v[2:3], v[6:7]
	v_mul_f32_e32 v3, v5, v5
	v_mul_f32_e32 v2, v7, v7
	v_fmac_f32_e32 v2, v6, v6
	v_fmac_f32_e32 v3, v4, v4
	v_add_f32_e32 v2, v2, v3
	v_add_f32_e32 v2, v10, v2
	ds_bpermute_b32 v3, v119, v2
	v_cvt_pk_bf16_f32 v218, v6, v7
	v_cvt_pk_bf16_f32 v219, v4, v5
	s_nop 1
	v_permlane16_swap_b32_e32 v216, v218
	v_permlane16_swap_b32_e32 v217, v219
	v_lshl_add_u64 v[220:221], v[20:21], 0, v[248:249]
	global_store_dwordx4 v[220:221], v[216:219], off offset:256
	s_waitcnt lgkmcnt(0)
	v_add_f32_e32 v2, v2, v3
	ds_bpermute_b32 v3, v116, v2
	s_and_saveexec_b64 s[44:45], s[4:5]
	s_cbranch_execz .LBB0_1289
	v_lshlrev_b64 v[4:5], 6, v[18:19]
	v_lshl_add_u64 v[4:5], s[12:13], 0, v[4:5]
	v_lshl_add_u64 v[4:5], s[38:39], 2, v[4:5]
	s_lshl_b32 s18, s57, 2
	v_lshl_add_u64 v[4:5], v[4:5], 0, s[18:19]
	s_waitcnt lgkmcnt(0)
	v_add_f32_e32 v2, v2, v3
	global_store_dword v[4:5], v2, off

.LBB0_1363:
	s_lshl_b32 s1, s26, 8
	v_add_u32_e32 v148, s1, v1
	v_ashrrev_i32_e32 v149, 31, v148
	v_lshlrev_b64 v[146:147], 6, v[148:149]
	v_lshl_add_u64 v[146:147], s[12:13], 0, v[146:147]
	v_mov_b32_e32 v246, v146
	v_mov_b32_e32 v247, v147
	v_add_co_u32_e32 v248, vcc, 0x2000, v146
	s_nop 1
	v_addc_co_u32_e32 v249, vcc, 0, v147, vcc
	global_load_dwordx4 v[160:163], v[146:147], off
	global_load_dwordx4 v[164:167], v[146:147], off offset:16
	global_load_dwordx4 v[168:171], v[146:147], off offset:32
	global_load_dwordx4 v[172:175], v[146:147], off offset:48
	global_load_dwordx4 v[184:187], v[246:247], off offset:1024
	global_load_dwordx4 v[188:191], v[246:247], off offset:1040
	global_load_dwordx4 v[192:195], v[246:247], off offset:1056
	global_load_dwordx4 v[196:199], v[246:247], off offset:1072
	global_load_dwordx4 v[200:203], v[246:247], off offset:2048
	global_load_dwordx4 v[204:207], v[246:247], off offset:2064
	global_load_dwordx4 v[208:211], v[246:247], off offset:2080
	global_load_dwordx4 v[212:215], v[246:247], off offset:2096
	global_load_dwordx4 v[230:233], v[246:247], off offset:3072
	global_load_dwordx4 v[234:237], v[246:247], off offset:3088
	global_load_dwordx4 v[238:241], v[246:247], off offset:3104
	global_load_dwordx4 v[242:245], v[246:247], off offset:3120
	v_mov_b32_e32 v181, v116
	v_mov_b32_e32 v116, v125
	v_mov_b32_e32 v178, v126
	v_mov_b32_e32 v179, v118
	v_mov_b32_e32 v118, v127
	v_mov_b32_e32 v126, v128
	v_mov_b32_e32 v127, v120
	v_mov_b32_e32 v120, v129
	v_mov_b32_e32 v128, v122
	v_mov_b32_e32 v129, v114
	v_mov_b32_e32 v114, v123
	v_mov_b32_e32 v180, v124
	v_lshl_or_b32 v176, s0, 7, v154
	v_mov_b64_e32 v[146:147], s[10:11]
	v_ashrrev_i32_e32 v177, 31, v176
	v_add_u32_e32 v182, s1, v151
	v_mad_i64_i32 v[124:125], s[2:3], v148, s52, v[146:147]
	v_lshlrev_b64 v[122:123], 1, v[176:177]
	v_ashrrev_i32_e32 v183, 31, v182
	v_lshl_add_u64 v[124:125], v[124:125], 0, v[122:123]
	s_andn2_b64 vcc, exec, s[4:5]
	s_mov_b64 s[4:5], -1
	s_waitcnt vmcnt(12)
	v_pk_add_f32 v[162:163], v[162:163], v[166:167]
	v_pk_add_f32 v[160:161], v[160:161], v[164:165]
	v_pk_add_f32 v[164:165], v[170:171], v[174:175]
	v_pk_add_f32 v[166:167], v[168:169], v[172:173]
	v_pk_add_f32 v[162:163], v[162:163], v[164:165]
	v_pk_add_f32 v[160:161], v[160:161], v[166:167]
	s_nop 0
	v_pk_mov_b32 v[164:165], v[160:161], v[162:163] op_sel:[1,0]
	v_mov_b32_e32 v161, v163
	v_pk_add_f32 v[160:161], v[164:165], v[160:161]
	v_lshlrev_b64 v[162:163], 6, v[182:183]
	v_add_f32_e32 v149, v160, v161
	v_fmamk_f32 v149, v149, 0x3a800000, v158
	v_rsq_f32_e32 v160, v149
	v_lshl_add_u64 v[162:163], s[12:13], 0, v[162:163]
	v_pk_mul_f32 v[116:117], v[116:117], v[160:161] op_sel_hi:[1,0]
	v_pk_mul_f32 v[164:165], v[178:179], v[160:161] op_sel_hi:[1,0]
	v_pk_mul_f32 v[118:119], v[118:119], v[160:161] op_sel_hi:[1,0]
	v_pk_mul_f32 v[126:127], v[126:127], v[160:161] op_sel_hi:[1,0]
	v_pk_mul_f32 v[120:121], v[120:121], v[160:161] op_sel_hi:[1,0]
	v_pk_mul_f32 v[128:129], v[128:129], v[160:161] op_sel_hi:[1,0]
	v_pk_mul_f32 v[114:115], v[114:115], v[160:161] op_sel_hi:[1,0]
	v_pk_mul_f32 v[166:167], v[180:181], v[160:161] op_sel_hi:[1,0]
	v_mul_f32_e32 v171, 0xbfb8aa3b, v117
	v_mul_f32_e32 v149, 0xbfb8aa3b, v165
	v_mul_f32_e32 v159, 0xbfb8aa3b, v119
	v_mul_f32_e32 v160, 0xbfb8aa3b, v127
	v_mul_f32_e32 v161, 0xbfb8aa3b, v121
	v_mul_f32_e32 v168, 0xbfb8aa3b, v129
	v_mul_f32_e32 v169, 0xbfb8aa3b, v115
	v_mul_f32_e32 v170, 0xbfb8aa3b, v167
	v_exp_f32_e32 v171, v171
	v_exp_f32_e32 v149, v149
	v_exp_f32_e32 v159, v159
	v_exp_f32_e32 v160, v160
	v_exp_f32_e32 v161, v161
	v_exp_f32_e32 v168, v168
	v_exp_f32_e32 v169, v169
	v_exp_f32_e32 v170, v170
	v_add_f32_e32 v171, 1.0, v171
	v_add_f32_e32 v149, 1.0, v149
	v_add_f32_e32 v159, 1.0, v159
	v_add_f32_e32 v160, 1.0, v160
	v_add_f32_e32 v161, 1.0, v161
	v_add_f32_e32 v168, 1.0, v168
	v_add_f32_e32 v169, 1.0, v169
	v_add_f32_e32 v170, 1.0, v170
	v_rcp_f32_e32 v171, v171
	v_rcp_f32_e32 v149, v149
	v_rcp_f32_e32 v159, v159
	v_rcp_f32_e32 v160, v160
	v_rcp_f32_e32 v161, v161
	v_rcp_f32_e32 v168, v168
	v_rcp_f32_e32 v169, v169
	v_rcp_f32_e32 v170, v170
	v_mul_f32_e32 v117, v117, v171
	v_mul_f32_e32 v149, v165, v149
	v_mul_f32_e32 v119, v119, v159
	v_mul_f32_e32 v127, v127, v160
	v_mul_f32_e32 v121, v121, v161
	v_mul_f32_e32 v129, v129, v168
	v_mul_f32_e32 v115, v115, v169
	v_mul_f32_e32 v159, v167, v170
	v_mul_f32_e32 v117, v116, v117
	v_mul_f32_e32 v149, v164, v149
	v_mul_f32_e32 v118, v118, v119
	v_mul_f32_e32 v119, v126, v127
	v_mul_f32_e32 v120, v120, v121
	v_mul_f32_e32 v121, v128, v129
	v_mul_f32_e32 v126, v114, v115
	v_mul_f32_e32 v127, v166, v159
	v_cvt_pk_bf16_f32 v114, v149, v118
	v_cvt_pk_bf16_f32 v115, v119, v120
	v_cvt_pk_bf16_f32 v116, v121, v126
	v_cvt_pk_bf16_f32 v117, v127, v117
	global_store_dwordx4 v[124:125], v[114:117], off
	s_nop 0
	s_nop 0
	v_mov_b32_e32 v129, v102
	v_mov_b32_e32 v102, v111
	v_mov_b32_e32 v111, v104
	v_mov_b32_e32 v104, v113
	v_mov_b32_e32 v113, v98
	v_mov_b32_e32 v98, v107
	v_mov_b32_e32 v107, v100
	v_mov_b32_e32 v100, v109
	v_mov_b32_e32 v128, v110
	v_mov_b32_e32 v110, v112
	v_mov_b32_e32 v112, v106
	v_mov_b32_e32 v106, v108
	v_add_u32_e32 v164, s1, v152
	v_mad_i64_i32 v[108:109], s[2:3], v182, s52, v[146:147]
	v_ashrrev_i32_e32 v165, 31, v164
	v_lshl_add_u64 v[108:109], v[108:109], 0, v[122:123]
	s_waitcnt vmcnt(9)
	v_pk_add_f32 v[116:117], v[186:187], v[190:191]
	v_pk_add_f32 v[114:115], v[184:185], v[188:189]
	v_pk_add_f32 v[118:119], v[194:195], v[198:199]
	v_pk_add_f32 v[120:121], v[192:193], v[196:197]
	v_pk_add_f32 v[116:117], v[116:117], v[118:119]
	v_pk_add_f32 v[114:115], v[114:115], v[120:121]
	s_nop 0
	v_pk_mov_b32 v[118:119], v[114:115], v[116:117] op_sel:[1,0]
	v_mov_b32_e32 v115, v117
	v_pk_add_f32 v[114:115], v[118:119], v[114:115]
	v_lshlrev_b64 v[116:117], 6, v[164:165]
	v_add_f32_e32 v114, v114, v115
	v_fmamk_f32 v114, v114, 0x3a800000, v158
	v_rsq_f32_e32 v114, v114
	v_lshl_add_u64 v[116:117], s[12:13], 0, v[116:117]
	v_pk_mul_f32 v[100:101], v[100:101], v[114:115] op_sel_hi:[1,0]
	v_pk_mul_f32 v[118:119], v[128:129], v[114:115] op_sel_hi:[1,0]
	v_pk_mul_f32 v[102:103], v[102:103], v[114:115] op_sel_hi:[1,0]
	v_pk_mul_f32 v[110:111], v[110:111], v[114:115] op_sel_hi:[1,0]
	v_pk_mul_f32 v[104:105], v[104:105], v[114:115] op_sel_hi:[1,0]
	v_pk_mul_f32 v[112:113], v[112:113], v[114:115] op_sel_hi:[1,0]
	v_pk_mul_f32 v[98:99], v[98:99], v[114:115] op_sel_hi:[1,0]
	v_pk_mul_f32 v[106:107], v[106:107], v[114:115] op_sel_hi:[1,0]
	v_mul_f32_e32 v127, 0xbfb8aa3b, v101
	v_mul_f32_e32 v114, 0xbfb8aa3b, v119
	v_mul_f32_e32 v115, 0xbfb8aa3b, v103
	v_mul_f32_e32 v120, 0xbfb8aa3b, v111
	v_mul_f32_e32 v121, 0xbfb8aa3b, v105
	v_mul_f32_e32 v124, 0xbfb8aa3b, v113
	v_mul_f32_e32 v125, 0xbfb8aa3b, v99
	v_mul_f32_e32 v126, 0xbfb8aa3b, v107
	v_exp_f32_e32 v127, v127
	v_exp_f32_e32 v114, v114
	v_exp_f32_e32 v115, v115
	v_exp_f32_e32 v120, v120
	v_exp_f32_e32 v121, v121
	v_exp_f32_e32 v124, v124
	v_exp_f32_e32 v125, v125
	v_exp_f32_e32 v126, v126
	v_add_f32_e32 v127, 1.0, v127
	v_add_f32_e32 v114, 1.0, v114
	v_add_f32_e32 v115, 1.0, v115
	v_add_f32_e32 v120, 1.0, v120
	v_add_f32_e32 v121, 1.0, v121
	v_add_f32_e32 v124, 1.0, v124
	v_add_f32_e32 v125, 1.0, v125
	v_add_f32_e32 v126, 1.0, v126
	v_rcp_f32_e32 v127, v127
	v_rcp_f32_e32 v114, v114
	v_rcp_f32_e32 v115, v115
	v_rcp_f32_e32 v120, v120
	v_rcp_f32_e32 v121, v121
	v_rcp_f32_e32 v124, v124
	v_rcp_f32_e32 v125, v125
	v_rcp_f32_e32 v126, v126
	v_mul_f32_e32 v101, v101, v127
	v_mul_f32_e32 v114, v119, v114
	v_mul_f32_e32 v103, v103, v115
	v_mul_f32_e32 v111, v111, v120
	v_mul_f32_e32 v105, v105, v121
	v_mul_f32_e32 v113, v113, v124
	v_mul_f32_e32 v99, v99, v125
	v_mul_f32_e32 v107, v107, v126
	v_mul_f32_e32 v101, v100, v101
	v_mul_f32_e32 v114, v118, v114
	v_mul_f32_e32 v102, v102, v103
	v_mul_f32_e32 v103, v110, v111
	v_mul_f32_e32 v104, v104, v105
	v_mul_f32_e32 v105, v112, v113
	v_mul_f32_e32 v110, v98, v99
	v_mul_f32_e32 v106, v106, v107
	v_cvt_pk_bf16_f32 v98, v114, v102
	v_cvt_pk_bf16_f32 v99, v103, v104
	v_cvt_pk_bf16_f32 v100, v105, v110
	v_cvt_pk_bf16_f32 v101, v106, v101
	global_store_dwordx4 v[108:109], v[98:101], off
	global_load_dwordx4 v[184:187], v[248:249], off offset:0
	global_load_dwordx4 v[188:191], v[248:249], off offset:16
	global_load_dwordx4 v[192:195], v[248:249], off offset:32
	global_load_dwordx4 v[196:199], v[248:249], off offset:48
	s_nop 0
	v_mov_b32_e32 v115, v86
	v_mov_b32_e32 v86, v95
	v_mov_b32_e32 v95, v88
	v_mov_b32_e32 v88, v97
	v_mov_b32_e32 v97, v82
	v_mov_b32_e32 v82, v91
	v_mov_b32_e32 v91, v84
	v_mov_b32_e32 v84, v93
	v_mov_b32_e32 v114, v94
	v_mov_b32_e32 v94, v96
	v_mov_b32_e32 v96, v90
	v_mov_b32_e32 v90, v92
	v_add_u32_e32 v116, s1, v153
	v_mad_i64_i32 v[92:93], s[0:1], v164, s52, v[146:147]
	v_ashrrev_i32_e32 v117, 31, v116
	v_lshl_add_u64 v[92:93], v[92:93], 0, v[122:123]
	s_waitcnt vmcnt(10)
	v_pk_add_f32 v[100:101], v[202:203], v[206:207]
	v_pk_add_f32 v[98:99], v[200:201], v[204:205]
	v_pk_add_f32 v[102:103], v[210:211], v[214:215]
	v_pk_add_f32 v[104:105], v[208:209], v[212:213]
	v_pk_add_f32 v[100:101], v[100:101], v[102:103]
	v_pk_add_f32 v[98:99], v[98:99], v[104:105]
	s_nop 0
	v_pk_mov_b32 v[102:103], v[98:99], v[100:101] op_sel:[1,0]
	v_mov_b32_e32 v99, v101
	v_pk_add_f32 v[98:99], v[102:103], v[98:99]
	v_lshlrev_b64 v[100:101], 6, v[116:117]
	v_add_f32_e32 v98, v98, v99
	v_fmamk_f32 v98, v98, 0x3a800000, v158
	v_rsq_f32_e32 v98, v98
	v_lshl_add_u64 v[100:101], s[12:13], 0, v[100:101]
	v_pk_mul_f32 v[84:85], v[84:85], v[98:99] op_sel_hi:[1,0]
	v_pk_mul_f32 v[102:103], v[114:115], v[98:99] op_sel_hi:[1,0]
	v_pk_mul_f32 v[86:87], v[86:87], v[98:99] op_sel_hi:[1,0]
	v_pk_mul_f32 v[94:95], v[94:95], v[98:99] op_sel_hi:[1,0]
	v_pk_mul_f32 v[88:89], v[88:89], v[98:99] op_sel_hi:[1,0]
	v_pk_mul_f32 v[96:97], v[96:97], v[98:99] op_sel_hi:[1,0]
	v_pk_mul_f32 v[82:83], v[82:83], v[98:99] op_sel_hi:[1,0]
	v_pk_mul_f32 v[90:91], v[90:91], v[98:99] op_sel_hi:[1,0]
	v_mul_f32_e32 v109, 0xbfb8aa3b, v85
	v_mul_f32_e32 v98, 0xbfb8aa3b, v103
	v_mul_f32_e32 v99, 0xbfb8aa3b, v87
	v_mul_f32_e32 v104, 0xbfb8aa3b, v95
	v_mul_f32_e32 v105, 0xbfb8aa3b, v89
	v_mul_f32_e32 v106, 0xbfb8aa3b, v97
	v_mul_f32_e32 v107, 0xbfb8aa3b, v83
	v_mul_f32_e32 v108, 0xbfb8aa3b, v91
	v_exp_f32_e32 v109, v109
	v_exp_f32_e32 v98, v98
	v_exp_f32_e32 v99, v99
	v_exp_f32_e32 v104, v104
	v_exp_f32_e32 v105, v105
	v_exp_f32_e32 v106, v106
	v_exp_f32_e32 v107, v107
	v_exp_f32_e32 v108, v108
	v_add_f32_e32 v109, 1.0, v109
	v_add_f32_e32 v98, 1.0, v98
	v_add_f32_e32 v99, 1.0, v99
	v_add_f32_e32 v104, 1.0, v104
	v_add_f32_e32 v105, 1.0, v105
	v_add_f32_e32 v106, 1.0, v106
	v_add_f32_e32 v107, 1.0, v107
	v_add_f32_e32 v108, 1.0, v108
	v_rcp_f32_e32 v109, v109
	v_rcp_f32_e32 v98, v98
	v_rcp_f32_e32 v99, v99
	v_rcp_f32_e32 v104, v104
	v_rcp_f32_e32 v105, v105
	v_rcp_f32_e32 v106, v106
	v_rcp_f32_e32 v107, v107
	v_rcp_f32_e32 v108, v108
	v_mul_f32_e32 v85, v85, v109
	v_mul_f32_e32 v98, v103, v98
	v_mul_f32_e32 v87, v87, v99
	v_mul_f32_e32 v95, v95, v104
	v_mul_f32_e32 v89, v89, v105
	v_mul_f32_e32 v97, v97, v106
	v_mul_f32_e32 v83, v83, v107
	v_mul_f32_e32 v91, v91, v108
	v_mul_f32_e32 v85, v84, v85
	v_mul_f32_e32 v98, v102, v98
	v_mul_f32_e32 v86, v86, v87
	v_mul_f32_e32 v87, v94, v95
	v_mul_f32_e32 v88, v88, v89
	v_mul_f32_e32 v89, v96, v97
	v_mul_f32_e32 v94, v82, v83
	v_mul_f32_e32 v90, v90, v91
	v_cvt_pk_bf16_f32 v82, v98, v86
	v_cvt_pk_bf16_f32 v83, v87, v88
	v_cvt_pk_bf16_f32 v84, v89, v94
	v_cvt_pk_bf16_f32 v85, v90, v85
	global_store_dwordx4 v[92:93], v[82:85], off
	global_load_dwordx4 v[200:203], v[248:249], off offset:1024
	global_load_dwordx4 v[204:207], v[248:249], off offset:1040
	global_load_dwordx4 v[208:211], v[248:249], off offset:1056
	global_load_dwordx4 v[212:215], v[248:249], off offset:1072
	s_nop 0
	v_mov_b32_e32 v99, v70
	v_mov_b32_e32 v70, v79
	v_mov_b32_e32 v79, v72
	v_mov_b32_e32 v72, v81
	v_mov_b32_e32 v81, v66
	v_mov_b32_e32 v66, v75
	v_mov_b32_e32 v75, v68
	v_mov_b32_e32 v68, v77
	v_mov_b32_e32 v98, v78
	v_mov_b32_e32 v78, v80
	v_mov_b32_e32 v80, v74
	v_mov_b32_e32 v74, v76
	v_add_u32_e32 v100, 0x80, v148
	v_mad_i64_i32 v[76:77], s[0:1], v116, s52, v[146:147]
	v_ashrrev_i32_e32 v101, 31, v100
	v_lshl_add_u64 v[76:77], v[76:77], 0, v[122:123]
	s_waitcnt vmcnt(11)
	v_pk_add_f32 v[84:85], v[232:233], v[236:237]
	v_pk_add_f32 v[82:83], v[230:231], v[234:235]
	v_pk_add_f32 v[86:87], v[240:241], v[244:245]
	v_pk_add_f32 v[88:89], v[238:239], v[242:243]
	v_pk_add_f32 v[84:85], v[84:85], v[86:87]
	v_pk_add_f32 v[82:83], v[82:83], v[88:89]
	s_nop 0
	v_pk_mov_b32 v[86:87], v[82:83], v[84:85] op_sel:[1,0]
	v_mov_b32_e32 v83, v85
	v_pk_add_f32 v[82:83], v[86:87], v[82:83]
	v_lshlrev_b64 v[84:85], 6, v[100:101]
	v_add_f32_e32 v82, v82, v83
	v_fmamk_f32 v82, v82, 0x3a800000, v158
	v_rsq_f32_e32 v82, v82
	v_lshl_add_u64 v[84:85], s[12:13], 0, v[84:85]
	v_pk_mul_f32 v[68:69], v[68:69], v[82:83] op_sel_hi:[1,0]
	v_pk_mul_f32 v[86:87], v[98:99], v[82:83] op_sel_hi:[1,0]
	v_pk_mul_f32 v[70:71], v[70:71], v[82:83] op_sel_hi:[1,0]
	v_pk_mul_f32 v[78:79], v[78:79], v[82:83] op_sel_hi:[1,0]
	v_pk_mul_f32 v[72:73], v[72:73], v[82:83] op_sel_hi:[1,0]
	v_pk_mul_f32 v[80:81], v[80:81], v[82:83] op_sel_hi:[1,0]
	v_pk_mul_f32 v[66:67], v[66:67], v[82:83] op_sel_hi:[1,0]
	v_pk_mul_f32 v[74:75], v[74:75], v[82:83] op_sel_hi:[1,0]
	v_mul_f32_e32 v93, 0xbfb8aa3b, v69
	v_mul_f32_e32 v82, 0xbfb8aa3b, v87
	v_mul_f32_e32 v83, 0xbfb8aa3b, v71
	v_mul_f32_e32 v88, 0xbfb8aa3b, v79
	v_mul_f32_e32 v89, 0xbfb8aa3b, v73
	v_mul_f32_e32 v90, 0xbfb8aa3b, v81
	v_mul_f32_e32 v91, 0xbfb8aa3b, v67
	v_mul_f32_e32 v92, 0xbfb8aa3b, v75
	v_exp_f32_e32 v93, v93
	v_exp_f32_e32 v82, v82
	v_exp_f32_e32 v83, v83
	v_exp_f32_e32 v88, v88
	v_exp_f32_e32 v89, v89
	v_exp_f32_e32 v90, v90
	v_exp_f32_e32 v91, v91
	v_exp_f32_e32 v92, v92
	v_add_f32_e32 v93, 1.0, v93
	v_add_f32_e32 v82, 1.0, v82
	v_add_f32_e32 v83, 1.0, v83
	v_add_f32_e32 v88, 1.0, v88
	v_add_f32_e32 v89, 1.0, v89
	v_add_f32_e32 v90, 1.0, v90
	v_add_f32_e32 v91, 1.0, v91
	v_add_f32_e32 v92, 1.0, v92
	v_rcp_f32_e32 v93, v93
	v_rcp_f32_e32 v82, v82
	v_rcp_f32_e32 v83, v83
	v_rcp_f32_e32 v88, v88
	v_rcp_f32_e32 v89, v89
	v_rcp_f32_e32 v90, v90
	v_rcp_f32_e32 v91, v91
	v_rcp_f32_e32 v92, v92
	v_mul_f32_e32 v69, v69, v93
	v_mul_f32_e32 v82, v87, v82
	v_mul_f32_e32 v71, v71, v83
	v_mul_f32_e32 v79, v79, v88
	v_mul_f32_e32 v73, v73, v89
	v_mul_f32_e32 v81, v81, v90
	v_mul_f32_e32 v67, v67, v91
	v_mul_f32_e32 v75, v75, v92
	v_mul_f32_e32 v69, v68, v69
	v_mul_f32_e32 v82, v86, v82
	v_mul_f32_e32 v70, v70, v71
	v_mul_f32_e32 v71, v78, v79
	v_mul_f32_e32 v72, v72, v73
	v_mul_f32_e32 v73, v80, v81
	v_mul_f32_e32 v78, v66, v67
	v_mul_f32_e32 v74, v74, v75
	v_cvt_pk_bf16_f32 v66, v82, v70
	v_cvt_pk_bf16_f32 v67, v71, v72
	v_cvt_pk_bf16_f32 v68, v73, v78
	v_cvt_pk_bf16_f32 v69, v74, v69
	global_store_dwordx4 v[76:77], v[66:69], off
	global_load_dwordx4 v[230:233], v[248:249], off offset:2048
	global_load_dwordx4 v[234:237], v[248:249], off offset:2064
	global_load_dwordx4 v[238:241], v[248:249], off offset:2080
	global_load_dwordx4 v[242:245], v[248:249], off offset:2096
	s_nop 0
	v_mov_b32_e32 v83, v54
	v_mov_b32_e32 v54, v63
	v_mov_b32_e32 v63, v56
	v_mov_b32_e32 v56, v65
	v_mov_b32_e32 v65, v50
	v_mov_b32_e32 v50, v59
	v_mov_b32_e32 v59, v52
	v_mov_b32_e32 v52, v61
	v_mov_b32_e32 v82, v62
	v_mov_b32_e32 v62, v64
	v_mov_b32_e32 v64, v58
	v_mov_b32_e32 v58, v60
	v_add_u32_e32 v84, 0x90, v148
	v_mad_i64_i32 v[60:61], s[0:1], v100, s52, v[146:147]
	v_ashrrev_i32_e32 v85, 31, v84
	v_lshl_add_u64 v[60:61], v[60:61], 0, v[122:123]
	s_waitcnt vmcnt(10)
	v_pk_add_f32 v[68:69], v[186:187], v[190:191]
	v_pk_add_f32 v[66:67], v[184:185], v[188:189]
	v_pk_add_f32 v[70:71], v[194:195], v[198:199]
	v_pk_add_f32 v[72:73], v[192:193], v[196:197]
	v_pk_add_f32 v[68:69], v[68:69], v[70:71]
	v_pk_add_f32 v[66:67], v[66:67], v[72:73]
	s_nop 0
	v_pk_mov_b32 v[70:71], v[66:67], v[68:69] op_sel:[1,0]
	v_mov_b32_e32 v67, v69
	v_pk_add_f32 v[66:67], v[70:71], v[66:67]
	v_lshlrev_b64 v[68:69], 6, v[84:85]
	v_add_f32_e32 v66, v66, v67
	v_fmamk_f32 v66, v66, 0x3a800000, v158
	v_rsq_f32_e32 v66, v66
	v_lshl_add_u64 v[68:69], s[12:13], 0, v[68:69]
	v_pk_mul_f32 v[52:53], v[52:53], v[66:67] op_sel_hi:[1,0]
	v_pk_mul_f32 v[70:71], v[82:83], v[66:67] op_sel_hi:[1,0]
	v_pk_mul_f32 v[54:55], v[54:55], v[66:67] op_sel_hi:[1,0]
	v_pk_mul_f32 v[62:63], v[62:63], v[66:67] op_sel_hi:[1,0]
	v_pk_mul_f32 v[56:57], v[56:57], v[66:67] op_sel_hi:[1,0]
	v_pk_mul_f32 v[64:65], v[64:65], v[66:67] op_sel_hi:[1,0]
	v_pk_mul_f32 v[50:51], v[50:51], v[66:67] op_sel_hi:[1,0]
	v_pk_mul_f32 v[58:59], v[58:59], v[66:67] op_sel_hi:[1,0]
	v_mul_f32_e32 v77, 0xbfb8aa3b, v53
	v_mul_f32_e32 v66, 0xbfb8aa3b, v71
	v_mul_f32_e32 v67, 0xbfb8aa3b, v55
	v_mul_f32_e32 v72, 0xbfb8aa3b, v63
	v_mul_f32_e32 v73, 0xbfb8aa3b, v57
	v_mul_f32_e32 v74, 0xbfb8aa3b, v65
	v_mul_f32_e32 v75, 0xbfb8aa3b, v51
	v_mul_f32_e32 v76, 0xbfb8aa3b, v59
	v_exp_f32_e32 v77, v77
	v_exp_f32_e32 v66, v66
	v_exp_f32_e32 v67, v67
	v_exp_f32_e32 v72, v72
	v_exp_f32_e32 v73, v73
	v_exp_f32_e32 v74, v74
	v_exp_f32_e32 v75, v75
	v_exp_f32_e32 v76, v76
	v_add_f32_e32 v77, 1.0, v77
	v_add_f32_e32 v66, 1.0, v66
	v_add_f32_e32 v67, 1.0, v67
	v_add_f32_e32 v72, 1.0, v72
	v_add_f32_e32 v73, 1.0, v73
	v_add_f32_e32 v74, 1.0, v74
	v_add_f32_e32 v75, 1.0, v75
	v_add_f32_e32 v76, 1.0, v76
	v_rcp_f32_e32 v77, v77
	v_rcp_f32_e32 v66, v66
	v_rcp_f32_e32 v67, v67
	v_rcp_f32_e32 v72, v72
	v_rcp_f32_e32 v73, v73
	v_rcp_f32_e32 v74, v74
	v_rcp_f32_e32 v75, v75
	v_rcp_f32_e32 v76, v76
	v_mul_f32_e32 v53, v53, v77
	v_mul_f32_e32 v66, v71, v66
	v_mul_f32_e32 v55, v55, v67
	v_mul_f32_e32 v63, v63, v72
	v_mul_f32_e32 v57, v57, v73
	v_mul_f32_e32 v65, v65, v74
	v_mul_f32_e32 v51, v51, v75
	v_mul_f32_e32 v59, v59, v76
	v_mul_f32_e32 v53, v52, v53
	v_mul_f32_e32 v66, v70, v66
	v_mul_f32_e32 v54, v54, v55
	v_mul_f32_e32 v55, v62, v63
	v_mul_f32_e32 v56, v56, v57
	v_mul_f32_e32 v57, v64, v65
	v_mul_f32_e32 v62, v50, v51
	v_mul_f32_e32 v58, v58, v59
	v_cvt_pk_bf16_f32 v50, v66, v54
	v_cvt_pk_bf16_f32 v51, v55, v56
	v_cvt_pk_bf16_f32 v52, v57, v62
	v_cvt_pk_bf16_f32 v53, v58, v53
	global_store_dwordx4 v[60:61], v[50:53], off
	global_load_dwordx4 v[184:187], v[248:249], off offset:3072
	global_load_dwordx4 v[188:191], v[248:249], off offset:3088
	global_load_dwordx4 v[192:195], v[248:249], off offset:3104
	global_load_dwordx4 v[196:199], v[248:249], off offset:3120
	s_nop 0
	v_mov_b32_e32 v67, v38
	v_mov_b32_e32 v38, v47
	v_mov_b32_e32 v47, v40
	v_mov_b32_e32 v40, v49
	v_mov_b32_e32 v49, v34
	v_mov_b32_e32 v34, v43
	v_mov_b32_e32 v43, v36
	v_mov_b32_e32 v36, v45
	v_mov_b32_e32 v66, v46
	v_mov_b32_e32 v46, v48
	v_mov_b32_e32 v48, v42
	v_mov_b32_e32 v42, v44
	v_add_u32_e32 v68, 0xa0, v148
	v_mad_i64_i32 v[44:45], s[0:1], v84, s52, v[146:147]
	v_ashrrev_i32_e32 v69, 31, v68
	v_lshl_add_u64 v[44:45], v[44:45], 0, v[122:123]
	s_waitcnt vmcnt(10)
	v_pk_add_f32 v[52:53], v[202:203], v[206:207]
	v_pk_add_f32 v[50:51], v[200:201], v[204:205]
	v_pk_add_f32 v[54:55], v[210:211], v[214:215]
	v_pk_add_f32 v[56:57], v[208:209], v[212:213]
	v_pk_add_f32 v[52:53], v[52:53], v[54:55]
	v_pk_add_f32 v[50:51], v[50:51], v[56:57]
	s_nop 0
	v_pk_mov_b32 v[54:55], v[50:51], v[52:53] op_sel:[1,0]
	v_mov_b32_e32 v51, v53
	v_pk_add_f32 v[50:51], v[54:55], v[50:51]
	v_lshlrev_b64 v[52:53], 6, v[68:69]
	v_add_f32_e32 v50, v50, v51
	v_fmamk_f32 v50, v50, 0x3a800000, v158
	v_rsq_f32_e32 v50, v50
	v_lshl_add_u64 v[52:53], s[12:13], 0, v[52:53]
	v_pk_mul_f32 v[36:37], v[36:37], v[50:51] op_sel_hi:[1,0]
	v_pk_mul_f32 v[54:55], v[66:67], v[50:51] op_sel_hi:[1,0]
	v_pk_mul_f32 v[38:39], v[38:39], v[50:51] op_sel_hi:[1,0]
	v_pk_mul_f32 v[46:47], v[46:47], v[50:51] op_sel_hi:[1,0]
	v_pk_mul_f32 v[40:41], v[40:41], v[50:51] op_sel_hi:[1,0]
	v_pk_mul_f32 v[48:49], v[48:49], v[50:51] op_sel_hi:[1,0]
	v_pk_mul_f32 v[34:35], v[34:35], v[50:51] op_sel_hi:[1,0]
	v_pk_mul_f32 v[42:43], v[42:43], v[50:51] op_sel_hi:[1,0]
	v_mul_f32_e32 v61, 0xbfb8aa3b, v37
	v_mul_f32_e32 v50, 0xbfb8aa3b, v55
	v_mul_f32_e32 v51, 0xbfb8aa3b, v39
	v_mul_f32_e32 v56, 0xbfb8aa3b, v47
	v_mul_f32_e32 v57, 0xbfb8aa3b, v41
	v_mul_f32_e32 v58, 0xbfb8aa3b, v49
	v_mul_f32_e32 v59, 0xbfb8aa3b, v35
	v_mul_f32_e32 v60, 0xbfb8aa3b, v43
	v_exp_f32_e32 v61, v61
	v_exp_f32_e32 v50, v50
	v_exp_f32_e32 v51, v51
	v_exp_f32_e32 v56, v56
	v_exp_f32_e32 v57, v57
	v_exp_f32_e32 v58, v58
	v_exp_f32_e32 v59, v59
	v_exp_f32_e32 v60, v60
	v_add_f32_e32 v61, 1.0, v61
	v_add_f32_e32 v50, 1.0, v50
	v_add_f32_e32 v51, 1.0, v51
	v_add_f32_e32 v56, 1.0, v56
	v_add_f32_e32 v57, 1.0, v57
	v_add_f32_e32 v58, 1.0, v58
	v_add_f32_e32 v59, 1.0, v59
	v_add_f32_e32 v60, 1.0, v60
	v_rcp_f32_e32 v61, v61
	v_rcp_f32_e32 v50, v50
	v_rcp_f32_e32 v51, v51
	v_rcp_f32_e32 v56, v56
	v_rcp_f32_e32 v57, v57
	v_rcp_f32_e32 v58, v58
	v_rcp_f32_e32 v59, v59
	v_rcp_f32_e32 v60, v60
	v_mul_f32_e32 v37, v37, v61
	v_mul_f32_e32 v50, v55, v50
	v_mul_f32_e32 v39, v39, v51
	v_mul_f32_e32 v47, v47, v56
	v_mul_f32_e32 v41, v41, v57
	v_mul_f32_e32 v49, v49, v58
	v_mul_f32_e32 v35, v35, v59
	v_mul_f32_e32 v43, v43, v60
	v_mul_f32_e32 v37, v36, v37
	v_mul_f32_e32 v50, v54, v50
	v_mul_f32_e32 v38, v38, v39
	v_mul_f32_e32 v39, v46, v47
	v_mul_f32_e32 v40, v40, v41
	v_mul_f32_e32 v41, v48, v49
	v_mul_f32_e32 v46, v34, v35
	v_mul_f32_e32 v42, v42, v43
	v_cvt_pk_bf16_f32 v34, v50, v38
	v_cvt_pk_bf16_f32 v35, v39, v40
	v_cvt_pk_bf16_f32 v36, v41, v46
	v_cvt_pk_bf16_f32 v37, v42, v37
	global_store_dwordx4 v[44:45], v[34:37], off
	s_nop 0
	v_mov_b32_e32 v51, v22
	v_mov_b32_e32 v22, v31
	v_mov_b32_e32 v31, v24
	v_mov_b32_e32 v24, v33
	v_mov_b32_e32 v33, v18
	v_mov_b32_e32 v18, v27
	v_mov_b32_e32 v27, v20
	v_mov_b32_e32 v20, v29
	v_mov_b32_e32 v50, v30
	v_mov_b32_e32 v30, v32
	v_mov_b32_e32 v32, v26
	v_mov_b32_e32 v26, v28
	v_add_u32_e32 v52, 0xb0, v148
	v_mad_i64_i32 v[28:29], s[0:1], v68, s52, v[146:147]
	v_ashrrev_i32_e32 v53, 31, v52
	v_lshl_add_u64 v[28:29], v[28:29], 0, v[122:123]
	s_waitcnt vmcnt(6)
	v_pk_add_f32 v[36:37], v[232:233], v[236:237]
	v_pk_add_f32 v[34:35], v[230:231], v[234:235]
	v_pk_add_f32 v[38:39], v[240:241], v[244:245]
	v_pk_add_f32 v[40:41], v[238:239], v[242:243]
	v_pk_add_f32 v[36:37], v[36:37], v[38:39]
	v_pk_add_f32 v[34:35], v[34:35], v[40:41]
	s_nop 0
	v_pk_mov_b32 v[38:39], v[34:35], v[36:37] op_sel:[1,0]
	v_mov_b32_e32 v35, v37
	v_pk_add_f32 v[34:35], v[38:39], v[34:35]
	v_lshlrev_b64 v[36:37], 6, v[52:53]
	v_add_f32_e32 v34, v34, v35
	v_fmamk_f32 v34, v34, 0x3a800000, v158
	v_rsq_f32_e32 v34, v34
	v_lshl_add_u64 v[36:37], s[12:13], 0, v[36:37]
	v_pk_mul_f32 v[20:21], v[20:21], v[34:35] op_sel_hi:[1,0]
	v_pk_mul_f32 v[38:39], v[50:51], v[34:35] op_sel_hi:[1,0]
	v_pk_mul_f32 v[22:23], v[22:23], v[34:35] op_sel_hi:[1,0]
	v_pk_mul_f32 v[30:31], v[30:31], v[34:35] op_sel_hi:[1,0]
	v_pk_mul_f32 v[24:25], v[24:25], v[34:35] op_sel_hi:[1,0]
	v_pk_mul_f32 v[32:33], v[32:33], v[34:35] op_sel_hi:[1,0]
	v_pk_mul_f32 v[18:19], v[18:19], v[34:35] op_sel_hi:[1,0]
	v_pk_mul_f32 v[26:27], v[26:27], v[34:35] op_sel_hi:[1,0]
	v_mul_f32_e32 v45, 0xbfb8aa3b, v21
	v_mul_f32_e32 v34, 0xbfb8aa3b, v39
	v_mul_f32_e32 v35, 0xbfb8aa3b, v23
	v_mul_f32_e32 v40, 0xbfb8aa3b, v31
	v_mul_f32_e32 v41, 0xbfb8aa3b, v25
	v_mul_f32_e32 v42, 0xbfb8aa3b, v33
	v_mul_f32_e32 v43, 0xbfb8aa3b, v19
	v_mul_f32_e32 v44, 0xbfb8aa3b, v27
	v_exp_f32_e32 v45, v45
	v_exp_f32_e32 v34, v34
	v_exp_f32_e32 v35, v35
	v_exp_f32_e32 v40, v40
	v_exp_f32_e32 v41, v41
	v_exp_f32_e32 v42, v42
	v_exp_f32_e32 v43, v43
	v_exp_f32_e32 v44, v44
	v_add_f32_e32 v45, 1.0, v45
	v_add_f32_e32 v34, 1.0, v34
	v_add_f32_e32 v35, 1.0, v35
	v_add_f32_e32 v40, 1.0, v40
	v_add_f32_e32 v41, 1.0, v41
	v_add_f32_e32 v42, 1.0, v42
	v_add_f32_e32 v43, 1.0, v43
	v_add_f32_e32 v44, 1.0, v44
	v_rcp_f32_e32 v45, v45
	v_rcp_f32_e32 v34, v34
	v_rcp_f32_e32 v35, v35
	v_rcp_f32_e32 v40, v40
	v_rcp_f32_e32 v41, v41
	v_rcp_f32_e32 v42, v42
	v_rcp_f32_e32 v43, v43
	v_rcp_f32_e32 v44, v44
	v_mul_f32_e32 v21, v21, v45
	v_mul_f32_e32 v34, v39, v34
	v_mul_f32_e32 v23, v23, v35
	v_mul_f32_e32 v31, v31, v40
	v_mul_f32_e32 v25, v25, v41
	v_mul_f32_e32 v33, v33, v42
	v_mul_f32_e32 v19, v19, v43
	v_mul_f32_e32 v27, v27, v44
	v_mul_f32_e32 v21, v20, v21
	v_mul_f32_e32 v34, v38, v34
	v_mul_f32_e32 v22, v22, v23
	v_mul_f32_e32 v23, v30, v31
	v_mul_f32_e32 v24, v24, v25
	v_mul_f32_e32 v25, v32, v33
	v_mul_f32_e32 v30, v18, v19
	v_mul_f32_e32 v26, v26, v27
	v_cvt_pk_bf16_f32 v18, v34, v22
	v_cvt_pk_bf16_f32 v19, v23, v24
	v_cvt_pk_bf16_f32 v20, v25, v30
	v_cvt_pk_bf16_f32 v21, v26, v21
	global_store_dwordx4 v[28:29], v[18:21], off
	s_nop 0
	v_mov_b32_e32 v34, v14
	v_mov_b32_e32 v35, v10
	v_mov_b32_e32 v10, v15
	v_mov_b32_e32 v14, v16
	v_mov_b32_e32 v15, v12
	v_mov_b32_e32 v12, v17
	v_mov_b32_e32 v16, v6
	v_mov_b32_e32 v17, v2
	v_mov_b32_e32 v2, v7
	v_mov_b32_e32 v6, v8
	v_mov_b32_e32 v7, v4
	v_mov_b32_e32 v4, v9
	s_waitcnt vmcnt(2)
	v_pk_add_f32 v[8:9], v[186:187], v[190:191]
	v_pk_add_f32 v[18:19], v[184:185], v[188:189]
	v_pk_add_f32 v[20:21], v[194:195], v[198:199]
	v_pk_add_f32 v[22:23], v[192:193], v[196:197]
	v_pk_add_f32 v[8:9], v[8:9], v[20:21]
	v_pk_add_f32 v[18:19], v[18:19], v[22:23]
	s_nop 0
	v_pk_mov_b32 v[20:21], v[18:19], v[8:9] op_sel:[1,0]
	v_mov_b32_e32 v19, v9
	v_pk_add_f32 v[8:9], v[20:21], v[18:19]
	v_mad_i64_i32 v[18:19], s[0:1], v52, s52, v[146:147]
	v_add_f32_e32 v8, v8, v9
	v_fmamk_f32 v8, v8, 0x3a800000, v158
	v_rsq_f32_e32 v8, v8
	v_lshl_add_u64 v[18:19], v[18:19], 0, v[122:123]
	v_pk_mul_f32 v[4:5], v[4:5], v[8:9] op_sel_hi:[1,0]
	v_pk_mul_f32 v[20:21], v[34:35], v[8:9] op_sel_hi:[1,0]
	v_pk_mul_f32 v[10:11], v[10:11], v[8:9] op_sel_hi:[1,0]
	v_pk_mul_f32 v[14:15], v[14:15], v[8:9] op_sel_hi:[1,0]
	v_pk_mul_f32 v[12:13], v[12:13], v[8:9] op_sel_hi:[1,0]
	v_pk_mul_f32 v[16:17], v[16:17], v[8:9] op_sel_hi:[1,0]
	v_pk_mul_f32 v[2:3], v[2:3], v[8:9] op_sel_hi:[1,0]
	v_pk_mul_f32 v[6:7], v[6:7], v[8:9] op_sel_hi:[1,0]
	v_mul_f32_e32 v27, 0xbfb8aa3b, v5
	v_mul_f32_e32 v8, 0xbfb8aa3b, v21
	v_mul_f32_e32 v9, 0xbfb8aa3b, v11
	v_mul_f32_e32 v22, 0xbfb8aa3b, v15
	v_mul_f32_e32 v23, 0xbfb8aa3b, v13
	v_mul_f32_e32 v24, 0xbfb8aa3b, v17
	v_mul_f32_e32 v25, 0xbfb8aa3b, v3
	v_mul_f32_e32 v26, 0xbfb8aa3b, v7
	v_exp_f32_e32 v27, v27
	v_exp_f32_e32 v8, v8
	v_exp_f32_e32 v9, v9
	v_exp_f32_e32 v22, v22
	v_exp_f32_e32 v23, v23
	v_exp_f32_e32 v24, v24
	v_exp_f32_e32 v25, v25
	v_exp_f32_e32 v26, v26
	v_add_f32_e32 v27, 1.0, v27
	v_add_f32_e32 v8, 1.0, v8
	v_add_f32_e32 v9, 1.0, v9
	v_add_f32_e32 v22, 1.0, v22
	v_add_f32_e32 v23, 1.0, v23
	v_add_f32_e32 v24, 1.0, v24
	v_add_f32_e32 v25, 1.0, v25
	v_add_f32_e32 v26, 1.0, v26
	v_rcp_f32_e32 v27, v27
	v_rcp_f32_e32 v8, v8
	v_rcp_f32_e32 v9, v9
	v_rcp_f32_e32 v22, v22
	v_rcp_f32_e32 v23, v23
	v_rcp_f32_e32 v24, v24
	v_rcp_f32_e32 v25, v25
	v_rcp_f32_e32 v26, v26
	v_mul_f32_e32 v5, v5, v27
	v_mul_f32_e32 v8, v21, v8
	v_mul_f32_e32 v9, v11, v9
	v_mul_f32_e32 v11, v15, v22
	v_mul_f32_e32 v13, v13, v23
	v_mul_f32_e32 v15, v17, v24
	v_mul_f32_e32 v3, v3, v25
	v_mul_f32_e32 v7, v7, v26
	v_mul_f32_e32 v5, v4, v5
	v_mul_f32_e32 v8, v20, v8
	v_mul_f32_e32 v9, v10, v9
	v_mul_f32_e32 v10, v14, v11
	v_mul_f32_e32 v11, v12, v13
	v_mul_f32_e32 v12, v16, v15
	v_mul_f32_e32 v13, v2, v3
	v_mul_f32_e32 v6, v6, v7
	v_cvt_pk_bf16_f32 v2, v8, v9
	v_cvt_pk_bf16_f32 v3, v10, v11
	v_cvt_pk_bf16_f32 v4, v12, v13
	v_cvt_pk_bf16_f32 v5, v6, v5
	global_store_dwordx4 v[18:19], v[2:5], off
	s_cbranch_vccnz .LBB0_1356
	s_andn2_b64 vcc, exec, s[6:7]
	s_cbranch_vccnz .LBB0_1355
	s_barrier
	s_branch .LBB0_1355
